# L6 GEMM k-loop: next k-tile loads issued early in the iteration (B right after the LDS barrier into private registers, A after the k-half-0 MFMAs), single vmcnt(0) before ds_writes
# baseline (speedup 1.0000x reference)
.LBB0_1136:
	s_mov_b32 s54, 0xf600000
	s_mov_b32 s55, 0
	s_mov_b32 s56, 0xf610000
	s_mov_b32 s57, 0
	s_mov_b32 s58, 0xf620000
	s_mov_b32 s59, 0
	s_mov_b32 s60, 0xf630000
	s_mov_b32 s61, 0
	s_mov_b32 s62, 0xf640000
	s_mov_b32 s63, 0
	s_mov_b32 s64, 0xf650000
	s_mov_b32 s65, 0
	s_mov_b32 s66, 0x11c80000
	s_mov_b32 s67, 0
	s_mov_b32 s68, 0x11c90000
	s_mov_b32 s69, 0
	s_mov_b32 s70, 0x11ca0000
	s_mov_b32 s71, 0
	s_mov_b32 s72, 0x11cb0000
	s_mov_b32 s73, 0
	s_add_i32 s0, s5, s7
	s_ashr_i32 s1, s0, 31
	s_lshr_b32 s1, s1, 29
	s_add_i32 s1, s0, s1
	s_lshr_b32 s2, s1, 3
	s_and_b32 s1, s1, 0x1fffff8
	s_sub_i32 s0, s0, s1
	s_mul_i32 s1, s2, 0xc0
	v_add_u32_e32 v0, s1, v151
	v_ashrrev_i32_e32 v1, 31, v0
	v_lshlrev_b64 v[0:1], 11, v[0:1]
	v_lshl_add_u64 v[2:3], v[152:153], 0, v[0:1]
	s_mov_b32 s2, 0x10000
	v_add_co_u32_e32 v6, vcc, s2, v2
	s_mov_b32 s3, 0x20000
	s_nop 0
	v_addc_co_u32_e32 v7, vcc, 0, v3, vcc
	global_load_dwordx4 v[96:99], v[2:3], off
	global_load_dwordx4 v[100:103], v[6:7], off
	v_add_co_u32_e32 v6, vcc, s3, v2
	s_mov_b32 s3, 0x30000
	s_nop 0
	v_addc_co_u32_e32 v7, vcc, 0, v3, vcc
	s_waitcnt vmcnt(7)
	v_add_co_u32_e32 v8, vcc, s3, v2
	s_mov_b32 s3, 0x40000
	s_nop 0
	v_addc_co_u32_e32 v9, vcc, 0, v3, vcc
	s_lshl_b32 s0, s0, 7
	global_load_dwordx4 v[104:107], v[6:7], off
	global_load_dwordx4 v[108:111], v[8:9], off
	v_add_co_u32_e32 v6, vcc, s3, v2
	v_add_u32_e32 v4, s0, v151
	s_nop 0
	v_addc_co_u32_e32 v7, vcc, 0, v3, vcc
	v_ashrrev_i32_e32 v5, 31, v4
	v_add_co_u32_e32 v2, vcc, 0x50000, v2
	v_lshlrev_b64 v[4:5], 11, v[4:5]
	s_nop 0
	v_addc_co_u32_e32 v3, vcc, 0, v3, vcc
	global_load_dwordx4 v[112:115], v[6:7], off
	global_load_dwordx4 v[116:119], v[2:3], off
	v_lshl_add_u64 v[2:3], v[154:155], 0, v[4:5]
	v_add_co_u32_e32 v6, vcc, s2, v2
	v_mov_b32_e32 v92, 0
	s_nop 0
	v_addc_co_u32_e32 v7, vcc, 0, v3, vcc
	global_load_dwordx4 v[220:223], v[2:3], off
	global_load_dwordx4 v[234:237], v[6:7], off
	v_add_co_u32_e32 v6, vcc, 0x20000, v2
	v_lshl_add_u64 v[162:163], v[156:157], 0, v[0:1]
	s_nop 0
	v_addc_co_u32_e32 v7, vcc, 0, v3, vcc
	v_add_co_u32_e32 v2, vcc, 0x30000, v2
	v_lshl_add_u64 v[164:165], v[158:159], 0, v[4:5]
	s_nop 0
	v_addc_co_u32_e32 v3, vcc, 0, v3, vcc
	global_load_dwordx4 v[238:241], v[6:7], off
	global_load_dwordx4 v[242:245], v[2:3], off
	s_mov_b64 s[2:3], 0
	v_mov_b32_e32 v93, v92
	v_mov_b32_e32 v94, v92
	v_mov_b32_e32 v95, v92
	v_mov_b32_e32 v64, v92
	v_mov_b32_e32 v65, v92
	v_mov_b32_e32 v66, v92
	v_mov_b32_e32 v67, v92
	v_mov_b32_e32 v68, v92
	v_mov_b32_e32 v69, v92
	v_mov_b32_e32 v70, v92
	v_mov_b32_e32 v71, v92
	v_mov_b32_e32 v76, v92
	v_mov_b32_e32 v77, v92
	v_mov_b32_e32 v78, v92
	v_mov_b32_e32 v79, v92
	v_mov_b32_e32 v84, v92
	v_mov_b32_e32 v85, v92
	v_mov_b32_e32 v86, v92
	v_mov_b32_e32 v87, v92
	v_mov_b32_e32 v88, v92
	v_mov_b32_e32 v89, v92
	v_mov_b32_e32 v90, v92
	v_mov_b32_e32 v91, v92
	v_mov_b32_e32 v40, v92
	s_waitcnt vmcnt(13)
	v_mov_b32_e32 v41, v92
	v_mov_b32_e32 v42, v92
	v_mov_b32_e32 v43, v92
	v_mov_b32_e32 v28, v92
	v_mov_b32_e32 v29, v92
	v_mov_b32_e32 v30, v92
	v_mov_b32_e32 v31, v92
	v_mov_b32_e32 v44, v92
	v_mov_b32_e32 v45, v92
	v_mov_b32_e32 v46, v92
	v_mov_b32_e32 v47, v92
	v_mov_b32_e32 v32, v92
	v_mov_b32_e32 v33, v92
	v_mov_b32_e32 v34, v92
	v_mov_b32_e32 v35, v92
	v_mov_b32_e32 v16, v92
	v_mov_b32_e32 v17, v92
	v_mov_b32_e32 v18, v92
	v_mov_b32_e32 v19, v92
	v_mov_b32_e32 v4, v92
	v_mov_b32_e32 v5, v92
	v_mov_b32_e32 v6, v92
	v_mov_b32_e32 v7, v92
	s_waitcnt vmcnt(12)
	v_mov_b32_e32 v20, v92
	v_mov_b32_e32 v21, v92
	v_mov_b32_e32 v22, v92
	v_mov_b32_e32 v23, v92
	v_mov_b32_e32 v12, v92
	v_mov_b32_e32 v13, v92
	v_mov_b32_e32 v14, v92
	v_mov_b32_e32 v15, v92
	v_mov_b32_e32 v0, v92
	v_mov_b32_e32 v1, v92
	v_mov_b32_e32 v2, v92
	v_mov_b32_e32 v3, v92
	v_mov_b32_e32 v8, v92
	v_mov_b32_e32 v9, v92
	v_mov_b32_e32 v10, v92
	v_mov_b32_e32 v11, v92
	v_mov_b32_e32 v24, v92
	v_mov_b32_e32 v25, v92
	v_mov_b32_e32 v26, v92
	v_mov_b32_e32 v27, v92
	v_mov_b32_e32 v36, v92
	v_mov_b32_e32 v37, v92
	v_mov_b32_e32 v38, v92
	v_mov_b32_e32 v39, v92
	v_mov_b32_e32 v48, v92
	v_mov_b32_e32 v49, v92
	v_mov_b32_e32 v50, v92
	v_mov_b32_e32 v51, v92
	v_mov_b32_e32 v52, v92
	v_mov_b32_e32 v53, v92
	v_mov_b32_e32 v54, v92
	v_mov_b32_e32 v55, v92
	v_mov_b32_e32 v56, v92
	v_mov_b32_e32 v57, v92
	v_mov_b32_e32 v58, v92
	v_mov_b32_e32 v59, v92
	v_mov_b32_e32 v60, v92
	v_mov_b32_e32 v61, v92
	v_mov_b32_e32 v62, v92
	v_mov_b32_e32 v63, v92
	v_mov_b32_e32 v72, v92
	v_mov_b32_e32 v73, v92
	v_mov_b32_e32 v74, v92
	v_mov_b32_e32 v75, v92
	v_mov_b32_e32 v80, v92
	v_mov_b32_e32 v81, v92
	v_mov_b32_e32 v82, v92
	v_mov_b32_e32 v83, v92
.LBB0_1137:
	s_waitcnt vmcnt(0)
	ds_write_b128 v204, v[96:99]
	ds_write_b128 v204, v[100:103] offset:4608
	ds_write_b128 v204, v[104:107] offset:9216
	ds_write_b128 v204, v[108:111] offset:13824
	ds_write_b128 v204, v[112:115] offset:18432
	ds_write_b128 v204, v[116:119] offset:23040
	ds_write_b128 v204, v[220:223] offset:27648
	ds_write_b128 v204, v[234:237] offset:32256
	ds_write_b128 v204, v[238:241] offset:36864
	ds_write_b128 v204, v[242:245] offset:41472
	s_waitcnt lgkmcnt(0)
	s_barrier
	v_lshl_add_u64 v[224:225], v[164:165], 0, s[2:3]
	v_lshl_add_u64 v[224:225], v[224:225], 0, s[66:67]
	global_load_dwordx4 v[220:223], v[224:225], off offset:128
	v_lshl_add_u64 v[224:225], v[164:165], 0, s[2:3]
	v_lshl_add_u64 v[224:225], v[224:225], 0, s[68:69]
	global_load_dwordx4 v[234:237], v[224:225], off offset:128
	v_lshl_add_u64 v[224:225], v[164:165], 0, s[2:3]
	v_lshl_add_u64 v[224:225], v[224:225], 0, s[70:71]
	global_load_dwordx4 v[238:241], v[224:225], off offset:128
	v_lshl_add_u64 v[224:225], v[164:165], 0, s[2:3]
	v_lshl_add_u64 v[224:225], v[224:225], 0, s[72:73]
	global_load_dwordx4 v[242:245], v[224:225], off offset:128
	ds_read_b128 v[96:99], v206
	ds_read_b128 v[100:103], v205 offset:27648
	ds_read_b128 v[120:123], v205 offset:27712
	ds_read_b128 v[104:107], v206 offset:64
	ds_read_b128 v[108:111], v205 offset:29952
	ds_read_b128 v[132:135], v205 offset:30016
	ds_read_b128 v[112:115], v205 offset:32256
	ds_read_b128 v[208:211], v205 offset:32320
	ds_read_b128 v[116:119], v205 offset:34560
	ds_read_b128 v[136:139], v205 offset:34624
	s_waitcnt lgkmcnt(8)
	v_mfma_f32_16x16x32_bf16 v[80:83], v[96:99], v[100:103], v[80:83]
	s_waitcnt lgkmcnt(5)
	v_mfma_f32_16x16x32_bf16 v[72:75], v[96:99], v[108:111], v[72:75]
	s_waitcnt lgkmcnt(3)
	v_mfma_f32_16x16x32_bf16 v[60:63], v[96:99], v[112:115], v[60:63]
	s_waitcnt lgkmcnt(1)
	v_mfma_f32_16x16x32_bf16 v[56:59], v[96:99], v[116:119], v[56:59]
	ds_read_b128 v[96:99], v206 offset:2304
	ds_read_b128 v[124:127], v206 offset:2368
	s_waitcnt lgkmcnt(1)
	v_mfma_f32_16x16x32_bf16 v[52:55], v[96:99], v[100:103], v[52:55]
	v_mfma_f32_16x16x32_bf16 v[48:51], v[96:99], v[108:111], v[48:51]
	v_mfma_f32_16x16x32_bf16 v[36:39], v[96:99], v[112:115], v[36:39]
	v_mfma_f32_16x16x32_bf16 v[24:27], v[96:99], v[116:119], v[24:27]
	ds_read_b128 v[96:99], v206 offset:4608
	ds_read_b128 v[128:131], v206 offset:4672
	s_waitcnt lgkmcnt(1)
	v_mfma_f32_16x16x32_bf16 v[8:11], v[96:99], v[100:103], v[8:11]
	v_mfma_f32_16x16x32_bf16 v[0:3], v[96:99], v[108:111], v[0:3]
	v_mfma_f32_16x16x32_bf16 v[12:15], v[96:99], v[112:115], v[12:15]
	v_mfma_f32_16x16x32_bf16 v[20:23], v[96:99], v[116:119], v[20:23]
	ds_read_b128 v[96:99], v206 offset:6912
	ds_read_b128 v[212:215], v206 offset:6976
	s_waitcnt lgkmcnt(1)
	v_mfma_f32_16x16x32_bf16 v[4:7], v[96:99], v[100:103], v[4:7]
	v_mfma_f32_16x16x32_bf16 v[16:19], v[96:99], v[108:111], v[16:19]
	v_mfma_f32_16x16x32_bf16 v[32:35], v[96:99], v[112:115], v[32:35]
	v_mfma_f32_16x16x32_bf16 v[44:47], v[96:99], v[116:119], v[44:47]
	ds_read_b128 v[96:99], v206 offset:9216
	ds_read_b128 v[216:219], v206 offset:9280
	s_waitcnt lgkmcnt(1)
	v_mfma_f32_16x16x32_bf16 v[28:31], v[96:99], v[100:103], v[28:31]
	v_mfma_f32_16x16x32_bf16 v[40:43], v[96:99], v[108:111], v[40:43]
	v_mfma_f32_16x16x32_bf16 v[88:91], v[96:99], v[112:115], v[88:91]
	v_mfma_f32_16x16x32_bf16 v[84:87], v[96:99], v[116:119], v[84:87]
	ds_read_b128 v[96:99], v206 offset:11520
	ds_read_b128 v[140:143], v206 offset:11584
	s_waitcnt lgkmcnt(1)
	v_mfma_f32_16x16x32_bf16 v[76:79], v[96:99], v[100:103], v[76:79]
	v_mfma_f32_16x16x32_bf16 v[68:71], v[96:99], v[108:111], v[68:71]
	v_mfma_f32_16x16x32_bf16 v[64:67], v[96:99], v[112:115], v[64:67]
	v_mfma_f32_16x16x32_bf16 v[92:95], v[96:99], v[116:119], v[92:95]
	v_lshl_add_u64 v[224:225], v[162:163], 0, s[2:3]
	v_lshl_add_u64 v[224:225], v[224:225], 0, s[54:55]
	global_load_dwordx4 v[96:99], v[224:225], off offset:128
	v_lshl_add_u64 v[224:225], v[162:163], 0, s[2:3]
	v_lshl_add_u64 v[224:225], v[224:225], 0, s[56:57]
	global_load_dwordx4 v[100:103], v[224:225], off offset:128
	v_lshl_add_u64 v[224:225], v[162:163], 0, s[2:3]
	v_lshl_add_u64 v[224:225], v[224:225], 0, s[60:61]
	global_load_dwordx4 v[108:111], v[224:225], off offset:128
	v_lshl_add_u64 v[224:225], v[162:163], 0, s[2:3]
	v_lshl_add_u64 v[224:225], v[224:225], 0, s[62:63]
	global_load_dwordx4 v[112:115], v[224:225], off offset:128
	v_lshl_add_u64 v[224:225], v[162:163], 0, s[2:3]
	v_lshl_add_u64 v[224:225], v[224:225], 0, s[64:65]
	global_load_dwordx4 v[116:119], v[224:225], off offset:128
	v_mfma_f32_16x16x32_bf16 v[80:83], v[104:107], v[120:123], v[80:83]
	v_mfma_f32_16x16x32_bf16 v[72:75], v[104:107], v[132:135], v[72:75]
	v_mfma_f32_16x16x32_bf16 v[60:63], v[104:107], v[208:211], v[60:63]
	v_mfma_f32_16x16x32_bf16 v[56:59], v[104:107], v[136:139], v[56:59]
	v_lshl_add_u64 v[224:225], v[162:163], 0, s[2:3]
	v_lshl_add_u64 v[224:225], v[224:225], 0, s[58:59]
	global_load_dwordx4 v[104:107], v[224:225], off offset:128
	s_add_u32 s2, s2, 0x80
	s_addc_u32 s3, s3, 0
	s_cmpk_eq_i32 s2, 0x780
	v_mfma_f32_16x16x32_bf16 v[52:55], v[124:127], v[120:123], v[52:55]
	v_mfma_f32_16x16x32_bf16 v[48:51], v[124:127], v[132:135], v[48:51]
	v_mfma_f32_16x16x32_bf16 v[36:39], v[124:127], v[208:211], v[36:39]
	v_mfma_f32_16x16x32_bf16 v[24:27], v[124:127], v[136:139], v[24:27]
	v_mfma_f32_16x16x32_bf16 v[8:11], v[128:131], v[120:123], v[8:11]
	v_mfma_f32_16x16x32_bf16 v[0:3], v[128:131], v[132:135], v[0:3]
	v_mfma_f32_16x16x32_bf16 v[12:15], v[128:131], v[208:211], v[12:15]
	v_mfma_f32_16x16x32_bf16 v[20:23], v[128:131], v[136:139], v[20:23]
	v_mfma_f32_16x16x32_bf16 v[4:7], v[212:215], v[120:123], v[4:7]
	v_mfma_f32_16x16x32_bf16 v[16:19], v[212:215], v[132:135], v[16:19]
	v_mfma_f32_16x16x32_bf16 v[32:35], v[212:215], v[208:211], v[32:35]
	v_mfma_f32_16x16x32_bf16 v[44:47], v[212:215], v[136:139], v[44:47]
	v_mfma_f32_16x16x32_bf16 v[28:31], v[216:219], v[120:123], v[28:31]
	s_waitcnt lgkmcnt(0)
	v_mfma_f32_16x16x32_bf16 v[76:79], v[140:143], v[120:123], v[76:79]
	v_mfma_f32_16x16x32_bf16 v[40:43], v[216:219], v[132:135], v[40:43]
	v_mfma_f32_16x16x32_bf16 v[68:71], v[140:143], v[132:135], v[68:71]
	s_barrier
	v_mfma_f32_16x16x32_bf16 v[88:91], v[216:219], v[208:211], v[88:91]
	v_mfma_f32_16x16x32_bf16 v[84:87], v[216:219], v[136:139], v[84:87]
	v_mfma_f32_16x16x32_bf16 v[64:67], v[140:143], v[208:211], v[64:67]
	v_mfma_f32_16x16x32_bf16 v[92:95], v[140:143], v[136:139], v[92:95]
	s_cbranch_scc0 .LBB0_1137
	s_waitcnt vmcnt(0)
	ds_write_b128 v204, v[96:99]
	ds_write_b128 v204, v[100:103] offset:4608
	ds_write_b128 v204, v[104:107] offset:9216
	ds_write_b128 v204, v[108:111] offset:13824
	ds_write_b128 v204, v[112:115] offset:18432
	ds_write_b128 v204, v[116:119] offset:23040
	ds_write_b128 v204, v[220:223] offset:27648
	ds_write_b128 v204, v[234:237] offset:32256
	ds_write_b128 v204, v[238:241] offset:36864
	ds_write_b128 v204, v[242:245] offset:41472
	s_waitcnt lgkmcnt(0)
	s_barrier
	ds_read_b128 v[96:99], v205 offset:27648
	ds_read_b128 v[100:103], v205 offset:29952
	ds_read_b128 v[104:107], v205 offset:32256
	ds_read_b128 v[108:111], v205 offset:34560
	ds_read_b128 v[112:115], v206
	s_waitcnt lgkmcnt(0)
	v_mfma_f32_16x16x32_bf16 v[80:83], v[112:115], v[96:99], v[80:83]
	v_readlane_b32 s8, v251, 45
	s_movk_i32 s6, 0x1000
	v_readlane_b32 s9, v251, 46
	v_mfma_f32_16x16x32_bf16 v[72:75], v[112:115], v[100:103], v[72:75]
	v_readlane_b32 s10, v251, 47
	v_readlane_b32 s11, v251, 48
	v_mov_b32_e32 v161, v149
	v_mfma_f32_16x16x32_bf16 v[60:63], v[112:115], v[104:107], v[60:63]
	v_readlane_b32 s12, v251, 49
	v_readlane_b32 s14, v251, 51
	v_readlane_b32 s15, v251, 52
	v_mfma_f32_16x16x32_bf16 v[56:59], v[112:115], v[108:111], v[56:59]
	ds_read_b128 v[112:115], v206 offset:2304
	s_mov_b64 s[14:15], 0x12482000
	s_mov_b32 s12, 0x12482000
	s_waitcnt lgkmcnt(0)
	v_mfma_f32_16x16x32_bf16 v[52:55], v[112:115], v[96:99], v[52:55]
	s_movk_i32 s53, 0x1000
	v_readlane_b32 s13, v251, 50
	v_readlane_b32 s16, v251, 53
	v_mfma_f32_16x16x32_bf16 v[48:51], v[112:115], v[100:103], v[48:51]
	v_readlane_b32 s17, v251, 54
	v_readlane_b32 s18, v251, 55
	v_readlane_b32 s19, v251, 56
	v_mfma_f32_16x16x32_bf16 v[36:39], v[112:115], v[104:107], v[36:39]
	v_readlane_b32 s20, v251, 57
	v_readlane_b32 s21, v251, 58
	v_readlane_b32 s22, v251, 59
	v_mfma_f32_16x16x32_bf16 v[24:27], v[112:115], v[108:111], v[24:27]
	ds_read_b128 v[112:115], v206 offset:4608
	v_readlane_b32 s23, v251, 60
	s_waitcnt lgkmcnt(0)
	v_mfma_f32_16x16x32_bf16 v[8:11], v[112:115], v[96:99], v[8:11]
	v_mfma_f32_16x16x32_bf16 v[0:3], v[112:115], v[100:103], v[0:3]
	v_mfma_f32_16x16x32_bf16 v[12:15], v[112:115], v[104:107], v[12:15]
	v_mfma_f32_16x16x32_bf16 v[20:23], v[112:115], v[108:111], v[20:23]
	ds_read_b128 v[112:115], v206 offset:6912
	s_waitcnt lgkmcnt(0)
	v_mfma_f32_16x16x32_bf16 v[4:7], v[112:115], v[96:99], v[4:7]
	v_mfma_f32_16x16x32_bf16 v[16:19], v[112:115], v[100:103], v[16:19]
	v_mfma_f32_16x16x32_bf16 v[32:35], v[112:115], v[104:107], v[32:35]
	v_mfma_f32_16x16x32_bf16 v[112:115], v[112:115], v[108:111], v[44:47]
	s_nop 2
	ds_read_b128 v[44:47], v206 offset:9216
	s_waitcnt lgkmcnt(0)
	v_mfma_f32_16x16x32_bf16 v[116:119], v[44:47], v[100:103], v[40:43]
	s_nop 2
	ds_read_b128 v[40:43], v206 offset:11520
	v_mfma_f32_16x16x32_bf16 v[28:31], v[44:47], v[96:99], v[28:31]
	v_mfma_f32_16x16x32_bf16 v[120:123], v[44:47], v[104:107], v[88:91]
	v_mfma_f32_16x16x32_bf16 v[124:127], v[44:47], v[108:111], v[84:87]
	s_waitcnt lgkmcnt(0)
	v_mfma_f32_16x16x32_bf16 v[96:99], v[40:43], v[96:99], v[76:79]
	v_mfma_f32_16x16x32_bf16 v[100:103], v[40:43], v[100:103], v[68:71]
	v_mfma_f32_16x16x32_bf16 v[104:107], v[40:43], v[104:107], v[64:67]
	v_mfma_f32_16x16x32_bf16 v[108:111], v[40:43], v[108:111], v[92:95]
	ds_read_b128 v[128:131], v205 offset:27712
	ds_read_b128 v[132:135], v205 offset:30016
	ds_read_b128 v[136:139], v205 offset:32320
	ds_read_b128 v[140:143], v205 offset:34624
	ds_read_b128 v[40:43], v206 offset:64
	s_waitcnt lgkmcnt(0)
	v_mfma_f32_16x16x32_bf16 v[92:95], v[40:43], v[128:131], v[80:83]
	v_mfma_f32_16x16x32_bf16 v[88:91], v[40:43], v[132:135], v[72:75]
	v_mfma_f32_16x16x32_bf16 v[84:87], v[40:43], v[136:139], v[60:63]
	v_mfma_f32_16x16x32_bf16 v[80:83], v[40:43], v[140:143], v[56:59]
	ds_read_b128 v[40:43], v206 offset:2368
	s_waitcnt lgkmcnt(0)
	v_mfma_f32_16x16x32_bf16 v[64:67], v[40:43], v[140:143], v[24:27]
	s_nop 2
	ds_read_b128 v[24:27], v206 offset:4672
	s_waitcnt lgkmcnt(0)
	v_mfma_f32_16x16x32_bf16 v[56:59], v[24:27], v[132:135], v[0:3]
	s_nop 2
	ds_read_b128 v[0:3], v206 offset:6976
	v_mfma_f32_16x16x32_bf16 v[76:79], v[40:43], v[128:131], v[52:55]
	v_mfma_f32_16x16x32_bf16 v[72:75], v[40:43], v[132:135], v[48:51]
	v_mfma_f32_16x16x32_bf16 v[68:71], v[40:43], v[136:139], v[36:39]
	s_waitcnt lgkmcnt(0)
	v_mfma_f32_16x16x32_bf16 v[44:47], v[0:3], v[128:131], v[4:7]
	v_mfma_f32_16x16x32_bf16 v[40:43], v[0:3], v[132:135], v[16:19]
	v_mfma_f32_16x16x32_bf16 v[36:39], v[0:3], v[136:139], v[32:35]
	v_mfma_f32_16x16x32_bf16 v[32:35], v[0:3], v[140:143], v[112:115]
	ds_read_b128 v[0:3], v206 offset:9280
	v_mfma_f32_16x16x32_bf16 v[60:63], v[24:27], v[128:131], v[8:11]
	v_mfma_f32_16x16x32_bf16 v[52:55], v[24:27], v[136:139], v[12:15]
	v_mfma_f32_16x16x32_bf16 v[48:51], v[24:27], v[140:143], v[20:23]
	s_waitcnt lgkmcnt(0)
	v_mfma_f32_16x16x32_bf16 v[28:31], v[0:3], v[128:131], v[28:31]
	v_mfma_f32_16x16x32_bf16 v[24:27], v[0:3], v[132:135], v[116:119]
	v_mfma_f32_16x16x32_bf16 v[20:23], v[0:3], v[136:139], v[120:123]
	v_mfma_f32_16x16x32_bf16 v[16:19], v[0:3], v[140:143], v[124:127]
	ds_read_b128 v[0:3], v206 offset:11584
	s_waitcnt lgkmcnt(0)
	s_barrier
	v_mfma_f32_16x16x32_bf16 v[12:15], v[0:3], v[128:131], v[96:99]
	s_nop 2
	v_add_u32_e32 v98, s1, v166
	s_ashr_i32 s1, s0, 31
	v_add_u32_e32 v97, 0xfffff000, v98
	s_lshl_b64 s[0:1], s[0:1], 2
	v_or_b32_e32 v96, v98, v167
	v_lshrrev_b32_e32 v97, 12, v97
	v_mfma_f32_16x16x32_bf16 v[4:7], v[0:3], v[136:139], v[104:107]
	s_add_u32 s2, s82, s0
	v_add_u32_e32 v99, 1, v97
	v_ashrrev_i32_e32 v97, 31, v96
	v_add_u32_e32 v106, 0xfffff000, v96
	v_mov_b32_e32 v107, v149
	v_mfma_f32_16x16x32_bf16 v[8:11], v[0:3], v[132:135], v[100:103]
	s_addc_u32 s3, s83, s1
	v_lshlrev_b64 v[106:107], 12, v[106:107]
	v_cmp_gt_i32_e32 vcc, s6, v96
	v_lshlrev_b64 v[100:101], 12, v[96:97]
	v_lshl_add_u64 v[102:103], s[2:3], 0, v[100:101]
	v_lshl_add_u64 v[100:101], s[8:9], 0, v[100:101]
	v_lshl_add_u64 v[106:107], s[10:11], 0, v[106:107]
	v_cndmask_b32_e32 v101, v107, v101, vcc
	v_cndmask_b32_e32 v100, v106, v100, vcc
	v_cndmask_b32_e64 v97, v99, 0, vcc
	v_lshl_add_u64 v[100:101], v[100:101], 0, s[0:1]
	v_add_u32_e32 v97, s4, v97
	v_lshl_add_u64 v[104:105], v[102:103], 0, v[148:149]
	v_cndmask_b32_e64 v100, v102, v100, s[36:37]
	v_mul_lo_u32 v102, v97, s24
	v_cndmask_b32_e64 v101, v103, v101, s[36:37]
	v_ashrrev_i32_e32 v103, 31, v102
	v_lshl_add_u64 v[102:103], v[102:103], 2, s[82:83]
	v_lshl_add_u64 v[102:103], v[102:103], 0, s[0:1]
	v_lshl_add_u64 v[102:103], v[102:103], 0, v[148:149]
	v_lshl_add_u64 v[102:103], v[102:103], 0, v[160:161]
	v_lshl_add_u64 v[106:107], v[102:103], 0, s[14:15]
	v_lshl_add_u64 v[100:101], v[100:101], 0, v[148:149]
	v_add_co_u32_e32 v102, vcc, s12, v102
	v_lshl_add_u64 v[100:101], v[100:101], 0, v[160:161]
	s_nop 0
	v_addc_co_u32_e32 v103, vcc, 0, v103, vcc
	global_load_dword v112, v[100:101], off
	v_lshl_add_u64 v[104:105], v[104:105], 0, v[160:161]
	global_load_dword v116, v[102:103], off
	v_mfma_f32_16x16x32_bf16 v[0:3], v[0:3], v[140:143], v[108:111]
	s_add_i32 s5, s5, s92
	s_cmp_ge_i32 s5, s93
	global_load_dword v113, v[100:101], off offset:64
	global_load_dword v117, v[106:107], off offset:64
	global_load_dword v114, v[100:101], off offset:128
	global_load_dword v118, v[106:107], off offset:128
	global_load_dword v115, v[100:101], off offset:192
	global_load_dword v119, v[106:107], off offset:192
	v_mov_b32_e32 v120, v92
	v_mov_b32_e32 v121, v88
	v_mov_b32_e32 v122, v84
	v_mov_b32_e32 v123, v80
	v_mov_b64_e32 v[124:125], v[104:105]
	v_or_b32_e32 v100, 1, v96
	v_ashrrev_i32_e32 v101, 31, v100
	v_lshlrev_b64 v[102:103], 12, v[100:101]
	v_cmp_gt_i32_e32 vcc, s6, v100
	v_lshl_add_u64 v[100:101], s[8:9], 0, v[102:103]
	v_lshl_add_u64 v[104:105], s[2:3], 0, v[102:103]
	v_add_u32_e32 v102, 0xfffff001, v96
	v_mov_b32_e32 v103, v149
	v_lshlrev_b64 v[102:103], 12, v[102:103]
	v_cndmask_b32_e64 v80, v99, 0, vcc
	v_lshl_add_u64 v[102:103], s[10:11], 0, v[102:103]
	v_add_u32_e32 v80, s4, v80
	v_cndmask_b32_e32 v100, v102, v100, vcc
	v_mul_lo_u32 v102, v80, s24
	v_cndmask_b32_e32 v101, v103, v101, vcc
	v_ashrrev_i32_e32 v103, 31, v102
	v_lshl_add_u64 v[102:103], v[102:103], 2, s[82:83]
	v_lshl_add_u64 v[102:103], v[102:103], 0, s[0:1]
	v_lshl_add_u64 v[100:101], v[100:101], 0, s[0:1]
	v_lshl_add_u64 v[102:103], v[102:103], 0, v[148:149]
	v_cndmask_b32_e64 v101, v105, v101, s[36:37]
	v_cndmask_b32_e64 v100, v104, v100, s[36:37]
	v_lshl_add_u64 v[102:103], v[102:103], 0, v[160:161]
	v_lshl_add_u64 v[106:107], v[104:105], 0, v[148:149]
	v_lshl_add_u64 v[104:105], v[102:103], 0, s[14:15]
	v_lshl_add_u64 v[100:101], v[100:101], 0, v[148:149]
	v_add_co_u32_e32 v102, vcc, s12, v102
	v_lshl_add_u64 v[100:101], v[100:101], 0, v[160:161]
	s_nop 0
	v_addc_co_u32_e32 v103, vcc, 0, v103, vcc
	global_load_dword v126, v[100:101], off
	global_load_dword v130, v[102:103], off
	v_lshl_add_u64 v[106:107], v[106:107], 0, v[160:161]
	global_load_dword v127, v[100:101], off offset:64
	global_load_dword v131, v[104:105], off offset:64
	global_load_dword v128, v[100:101], off offset:128
	global_load_dword v132, v[104:105], off offset:128
	global_load_dword v129, v[100:101], off offset:192
	global_load_dword v133, v[104:105], off offset:192
	v_mov_b32_e32 v134, v93
	v_mov_b32_e32 v135, v89
	v_mov_b32_e32 v136, v85
	v_mov_b32_e32 v137, v81
	v_mov_b64_e32 v[138:139], v[106:107]
	v_or_b32_e32 v80, 2, v96
	v_ashrrev_i32_e32 v81, 31, v80
	v_lshlrev_b64 v[84:85], 12, v[80:81]
	v_lshl_add_u64 v[88:89], s[2:3], 0, v[84:85]
	v_cmp_gt_i32_e32 vcc, s6, v80
	v_lshl_add_u64 v[80:81], s[8:9], 0, v[84:85]
	v_add_u32_e32 v84, 0xfffff002, v96
	v_mov_b32_e32 v85, v149
	v_lshlrev_b64 v[84:85], 12, v[84:85]
	v_lshl_add_u64 v[84:85], s[10:11], 0, v[84:85]
	v_cndmask_b32_e32 v80, v84, v80, vcc
	v_cndmask_b32_e64 v84, v99, 0, vcc
	v_add_u32_e32 v84, s4, v84
	v_mul_lo_u32 v84, v84, s24
	v_cndmask_b32_e32 v81, v85, v81, vcc
	v_ashrrev_i32_e32 v85, 31, v84
	v_lshl_add_u64 v[84:85], v[84:85], 2, s[82:83]
	v_lshl_add_u64 v[84:85], v[84:85], 0, s[0:1]
	v_lshl_add_u64 v[80:81], v[80:81], 0, s[0:1]
	v_lshl_add_u64 v[84:85], v[84:85], 0, v[148:149]
	v_cndmask_b32_e64 v81, v89, v81, s[36:37]
	v_cndmask_b32_e64 v80, v88, v80, s[36:37]
	v_lshl_add_u64 v[84:85], v[84:85], 0, v[160:161]
	v_lshl_add_u64 v[92:93], v[88:89], 0, v[148:149]
	v_lshl_add_u64 v[88:89], v[84:85], 0, s[14:15]
	v_lshl_add_u64 v[80:81], v[80:81], 0, v[148:149]
	v_add_co_u32_e32 v84, vcc, s12, v84
	v_lshl_add_u64 v[80:81], v[80:81], 0, v[160:161]
	s_nop 0
	v_addc_co_u32_e32 v85, vcc, 0, v85, vcc
	global_load_dword v234, v[80:81], off
	v_lshl_add_u64 v[92:93], v[92:93], 0, v[160:161]
	global_load_dword v238, v[84:85], off
	global_load_dword v235, v[80:81], off offset:64
	global_load_dword v239, v[88:89], off offset:64
	global_load_dword v236, v[80:81], off offset:128
	global_load_dword v240, v[88:89], off offset:128
	global_load_dword v237, v[80:81], off offset:192
	global_load_dword v241, v[88:89], off offset:192
	v_mov_b32_e32 v242, v94
	v_mov_b32_e32 v243, v90
	v_mov_b32_e32 v244, v86
	v_mov_b32_e32 v245, v82
	v_mov_b64_e32 v[220:221], v[92:93]
	s_waitcnt vmcnt(16)
	v_fmac_f32_e32 v112, v120, v116
	v_fmac_f32_e32 v113, v121, v117
	v_fmac_f32_e32 v114, v122, v118
	v_fmac_f32_e32 v115, v123, v119
	global_store_dword v[124:125], v112, off
	global_store_dword v[124:125], v113, off offset:64
	global_store_dword v[124:125], v114, off offset:128
	global_store_dword v[124:125], v115, off offset:192
	v_or_b32_e32 v80, 3, v96
	v_ashrrev_i32_e32 v81, 31, v80
	v_lshlrev_b64 v[84:85], 12, v[80:81]
	v_lshl_add_u64 v[88:89], s[2:3], 0, v[84:85]
	v_cmp_gt_i32_e32 vcc, s6, v80
	v_lshl_add_u64 v[80:81], s[8:9], 0, v[84:85]
	v_add_u32_e32 v84, 0xfffff003, v96
	v_mov_b32_e32 v85, v149
	v_lshlrev_b64 v[84:85], 12, v[84:85]
	v_cndmask_b32_e64 v82, v99, 0, vcc
	v_lshl_add_u64 v[84:85], s[10:11], 0, v[84:85]
	v_add_u32_e32 v82, s4, v82
	v_cndmask_b32_e32 v80, v84, v80, vcc
	v_mul_lo_u32 v84, v82, s24
	v_cndmask_b32_e32 v81, v85, v81, vcc
	v_ashrrev_i32_e32 v85, 31, v84
	v_lshl_add_u64 v[84:85], v[84:85], 2, s[82:83]
	v_lshl_add_u64 v[84:85], v[84:85], 0, s[0:1]
	v_lshl_add_u64 v[80:81], v[80:81], 0, s[0:1]
	v_lshl_add_u64 v[84:85], v[84:85], 0, v[148:149]
	v_cndmask_b32_e64 v81, v89, v81, s[36:37]
	v_cndmask_b32_e64 v80, v88, v80, s[36:37]
	v_lshl_add_u64 v[84:85], v[84:85], 0, v[160:161]
	v_lshl_add_u64 v[92:93], v[88:89], 0, v[148:149]
	v_lshl_add_u64 v[88:89], v[84:85], 0, s[14:15]
	v_lshl_add_u64 v[80:81], v[80:81], 0, v[148:149]
	v_add_co_u32_e32 v84, vcc, s12, v84
	v_lshl_add_u64 v[80:81], v[80:81], 0, v[160:161]
	s_nop 0
	v_addc_co_u32_e32 v85, vcc, 0, v85, vcc
	global_load_dword v112, v[80:81], off
	v_lshl_add_u64 v[92:93], v[92:93], 0, v[160:161]
	global_load_dword v116, v[84:85], off
	global_load_dword v113, v[80:81], off offset:64
	global_load_dword v117, v[88:89], off offset:64
	global_load_dword v114, v[80:81], off offset:128
	global_load_dword v118, v[88:89], off offset:128
	global_load_dword v115, v[80:81], off offset:192
	global_load_dword v119, v[88:89], off offset:192
	v_mov_b32_e32 v120, v95
	v_mov_b32_e32 v121, v91
	v_mov_b32_e32 v122, v87
	v_mov_b32_e32 v123, v83
	v_mov_b64_e32 v[124:125], v[92:93]
	s_waitcnt vmcnt(20)
	v_fmac_f32_e32 v126, v134, v130
	v_fmac_f32_e32 v127, v135, v131
	v_fmac_f32_e32 v128, v136, v132
	v_fmac_f32_e32 v129, v137, v133
	global_store_dword v[138:139], v126, off
	global_store_dword v[138:139], v127, off offset:64
	global_store_dword v[138:139], v128, off offset:128
	global_store_dword v[138:139], v129, off offset:192
	v_or_b32_e32 v84, 16, v96
	v_ashrrev_i32_e32 v85, 31, v84
	v_lshlrev_b64 v[86:87], 12, v[84:85]
	v_lshl_add_u64 v[88:89], s[2:3], 0, v[86:87]
	v_cmp_gt_i32_e32 vcc, s6, v84
	v_lshl_add_u64 v[84:85], s[8:9], 0, v[86:87]
	v_add_u32_e32 v86, 0xfffff010, v96
	v_mov_b32_e32 v87, v149
	v_lshlrev_b64 v[86:87], 12, v[86:87]
	v_lshl_add_u64 v[86:87], s[10:11], 0, v[86:87]
	v_cndmask_b32_e32 v84, v86, v84, vcc
	v_cndmask_b32_e32 v85, v87, v85, vcc
	v_lshl_add_u64 v[84:85], v[84:85], 0, s[0:1]
	v_cndmask_b32_e64 v85, v89, v85, s[36:37]
	v_cndmask_b32_e64 v84, v88, v84, s[36:37]
	v_lshl_add_u64 v[84:85], v[84:85], 0, v[148:149]
	v_lshl_add_u64 v[84:85], v[84:85], 0, v[160:161]
	v_add_u32_e32 v80, 0xfffff010, v98
	v_lshrrev_b32_e32 v80, 12, v80
	v_add_u32_e32 v82, 1, v80
	v_cndmask_b32_e64 v83, v82, 0, vcc
	v_add_u32_e32 v83, s4, v83
	v_mul_lo_u32 v86, v83, s24
	v_ashrrev_i32_e32 v87, 31, v86
	v_lshl_add_u64 v[86:87], v[86:87], 2, s[82:83]
	v_lshl_add_u64 v[86:87], v[86:87], 0, s[0:1]
	v_lshl_add_u64 v[86:87], v[86:87], 0, v[148:149]
	v_lshl_add_u64 v[86:87], v[86:87], 0, v[160:161]
	v_lshl_add_u64 v[80:81], v[88:89], 0, v[148:149]
	v_lshl_add_u64 v[88:89], v[86:87], 0, s[14:15]
	v_add_co_u32_e32 v86, vcc, s12, v86
	global_load_dword v126, v[84:85], off
	s_nop 0
	v_addc_co_u32_e32 v87, vcc, 0, v87, vcc
	global_load_dword v130, v[86:87], off
	v_lshl_add_u64 v[80:81], v[80:81], 0, v[160:161]
	global_load_dword v127, v[84:85], off offset:64
	global_load_dword v131, v[88:89], off offset:64
	global_load_dword v128, v[84:85], off offset:128
	global_load_dword v132, v[88:89], off offset:128
	global_load_dword v129, v[84:85], off offset:192
	global_load_dword v133, v[88:89], off offset:192
	v_mov_b32_e32 v134, v76
	v_mov_b32_e32 v135, v72
	v_mov_b32_e32 v136, v68
	v_mov_b32_e32 v137, v64
	v_mov_b64_e32 v[138:139], v[80:81]
	s_waitcnt vmcnt(24)
	v_fmac_f32_e32 v234, v242, v238
	v_fmac_f32_e32 v235, v243, v239
	v_fmac_f32_e32 v236, v244, v240
	v_fmac_f32_e32 v237, v245, v241
	global_store_dword v[220:221], v234, off
	global_store_dword v[220:221], v235, off offset:64
	global_store_dword v[220:221], v236, off offset:128
	global_store_dword v[220:221], v237, off offset:192
	v_or_b32_e32 v80, 17, v96
	v_ashrrev_i32_e32 v81, 31, v80
	v_lshlrev_b64 v[84:85], 12, v[80:81]
	v_lshl_add_u64 v[86:87], s[2:3], 0, v[84:85]
	v_cmp_gt_i32_e32 vcc, s6, v80
	v_lshl_add_u64 v[80:81], s[8:9], 0, v[84:85]
	v_add_u32_e32 v84, 0xfffff011, v96
	v_mov_b32_e32 v85, v149
	v_lshlrev_b64 v[84:85], 12, v[84:85]
	v_cndmask_b32_e64 v64, v82, 0, vcc
	v_lshl_add_u64 v[84:85], s[10:11], 0, v[84:85]
	v_add_u32_e32 v64, s4, v64
	v_cndmask_b32_e32 v80, v84, v80, vcc
	v_mul_lo_u32 v84, v64, s24
	v_cndmask_b32_e32 v81, v85, v81, vcc
	v_ashrrev_i32_e32 v85, 31, v84
	v_lshl_add_u64 v[84:85], v[84:85], 2, s[82:83]
	v_lshl_add_u64 v[84:85], v[84:85], 0, s[0:1]
	v_lshl_add_u64 v[80:81], v[80:81], 0, s[0:1]
	v_lshl_add_u64 v[84:85], v[84:85], 0, v[148:149]
	v_cndmask_b32_e64 v81, v87, v81, s[36:37]
	v_cndmask_b32_e64 v80, v86, v80, s[36:37]
	v_lshl_add_u64 v[84:85], v[84:85], 0, v[160:161]
	v_lshl_add_u64 v[88:89], v[86:87], 0, v[148:149]
	v_lshl_add_u64 v[86:87], v[84:85], 0, s[14:15]
	v_lshl_add_u64 v[80:81], v[80:81], 0, v[148:149]
	v_add_co_u32_e32 v84, vcc, s12, v84
	v_lshl_add_u64 v[80:81], v[80:81], 0, v[160:161]
	s_nop 0
	v_addc_co_u32_e32 v85, vcc, 0, v85, vcc
	global_load_dword v234, v[80:81], off
	global_load_dword v238, v[84:85], off
	v_lshl_add_u64 v[88:89], v[88:89], 0, v[160:161]
	global_load_dword v235, v[80:81], off offset:64
	global_load_dword v239, v[86:87], off offset:64
	global_load_dword v236, v[80:81], off offset:128
	global_load_dword v240, v[86:87], off offset:128
	global_load_dword v237, v[80:81], off offset:192
	global_load_dword v241, v[86:87], off offset:192
	v_mov_b32_e32 v242, v77
	v_mov_b32_e32 v243, v73
	v_mov_b32_e32 v244, v69
	v_mov_b32_e32 v245, v65
	v_mov_b64_e32 v[220:221], v[88:89]
	s_waitcnt vmcnt(24)
	v_fmac_f32_e32 v112, v120, v116
	v_fmac_f32_e32 v113, v121, v117
	v_fmac_f32_e32 v114, v122, v118
	v_fmac_f32_e32 v115, v123, v119
	global_store_dword v[124:125], v112, off
	global_store_dword v[124:125], v113, off offset:64
	global_store_dword v[124:125], v114, off offset:128
	global_store_dword v[124:125], v115, off offset:192
	v_or_b32_e32 v64, 18, v96
	v_ashrrev_i32_e32 v65, 31, v64
	v_lshlrev_b64 v[68:69], 12, v[64:65]
	v_lshl_add_u64 v[72:73], s[2:3], 0, v[68:69]
	v_cmp_gt_i32_e32 vcc, s6, v64
	v_lshl_add_u64 v[64:65], s[8:9], 0, v[68:69]
	v_add_u32_e32 v68, 0xfffff012, v96
	v_mov_b32_e32 v69, v149
	v_lshlrev_b64 v[68:69], 12, v[68:69]
	v_lshl_add_u64 v[68:69], s[10:11], 0, v[68:69]
	v_cndmask_b32_e32 v64, v68, v64, vcc
	v_cndmask_b32_e64 v68, v82, 0, vcc
	v_add_u32_e32 v68, s4, v68
	v_mul_lo_u32 v68, v68, s24
	v_cndmask_b32_e32 v65, v69, v65, vcc
	v_ashrrev_i32_e32 v69, 31, v68
	v_lshl_add_u64 v[68:69], v[68:69], 2, s[82:83]
	v_lshl_add_u64 v[68:69], v[68:69], 0, s[0:1]
	v_lshl_add_u64 v[64:65], v[64:65], 0, s[0:1]
	v_lshl_add_u64 v[68:69], v[68:69], 0, v[148:149]
	v_cndmask_b32_e64 v65, v73, v65, s[36:37]
	v_cndmask_b32_e64 v64, v72, v64, s[36:37]
	v_lshl_add_u64 v[68:69], v[68:69], 0, v[160:161]
	v_lshl_add_u64 v[76:77], v[72:73], 0, v[148:149]
	v_lshl_add_u64 v[72:73], v[68:69], 0, s[14:15]
	v_lshl_add_u64 v[64:65], v[64:65], 0, v[148:149]
	v_add_co_u32_e32 v68, vcc, s12, v68
	v_lshl_add_u64 v[64:65], v[64:65], 0, v[160:161]
	s_nop 0
	v_addc_co_u32_e32 v69, vcc, 0, v69, vcc
	global_load_dword v112, v[64:65], off
	v_lshl_add_u64 v[76:77], v[76:77], 0, v[160:161]
	global_load_dword v116, v[68:69], off
	global_load_dword v113, v[64:65], off offset:64
	global_load_dword v117, v[72:73], off offset:64
	global_load_dword v114, v[64:65], off offset:128
	global_load_dword v118, v[72:73], off offset:128
	global_load_dword v115, v[64:65], off offset:192
	global_load_dword v119, v[72:73], off offset:192
	v_mov_b32_e32 v120, v78
	v_mov_b32_e32 v121, v74
	v_mov_b32_e32 v122, v70
	v_mov_b32_e32 v123, v66
	v_mov_b64_e32 v[124:125], v[76:77]
	s_waitcnt vmcnt(24)
	v_fmac_f32_e32 v126, v134, v130
	v_fmac_f32_e32 v127, v135, v131
	v_fmac_f32_e32 v128, v136, v132
	v_fmac_f32_e32 v129, v137, v133
	global_store_dword v[138:139], v126, off
	global_store_dword v[138:139], v127, off offset:64
	global_store_dword v[138:139], v128, off offset:128
	global_store_dword v[138:139], v129, off offset:192
	v_or_b32_e32 v64, 19, v96
	v_ashrrev_i32_e32 v65, 31, v64
	v_lshlrev_b64 v[68:69], 12, v[64:65]
	v_lshl_add_u64 v[72:73], s[2:3], 0, v[68:69]
	v_cmp_gt_i32_e32 vcc, s6, v64
	v_lshl_add_u64 v[64:65], s[8:9], 0, v[68:69]
	v_add_u32_e32 v68, 0xfffff013, v96
	v_mov_b32_e32 v69, v149
	v_lshlrev_b64 v[68:69], 12, v[68:69]
	v_cndmask_b32_e64 v66, v82, 0, vcc
	v_lshl_add_u64 v[68:69], s[10:11], 0, v[68:69]
	v_add_u32_e32 v66, s4, v66
	v_cndmask_b32_e32 v64, v68, v64, vcc
	v_mul_lo_u32 v68, v66, s24
	v_cndmask_b32_e32 v65, v69, v65, vcc
	v_ashrrev_i32_e32 v69, 31, v68
	v_lshl_add_u64 v[68:69], v[68:69], 2, s[82:83]
	v_lshl_add_u64 v[68:69], v[68:69], 0, s[0:1]
	v_lshl_add_u64 v[64:65], v[64:65], 0, s[0:1]
	v_lshl_add_u64 v[68:69], v[68:69], 0, v[148:149]
	v_cndmask_b32_e64 v65, v73, v65, s[36:37]
	v_cndmask_b32_e64 v64, v72, v64, s[36:37]
	v_lshl_add_u64 v[68:69], v[68:69], 0, v[160:161]
	v_lshl_add_u64 v[76:77], v[72:73], 0, v[148:149]
	v_lshl_add_u64 v[72:73], v[68:69], 0, s[14:15]
	v_lshl_add_u64 v[64:65], v[64:65], 0, v[148:149]
	v_add_co_u32_e32 v68, vcc, s12, v68
	v_lshl_add_u64 v[64:65], v[64:65], 0, v[160:161]
	s_nop 0
	v_addc_co_u32_e32 v69, vcc, 0, v69, vcc
	global_load_dword v126, v[64:65], off
	v_lshl_add_u64 v[76:77], v[76:77], 0, v[160:161]
	global_load_dword v130, v[68:69], off
	global_load_dword v127, v[64:65], off offset:64
	global_load_dword v131, v[72:73], off offset:64
	global_load_dword v128, v[64:65], off offset:128
	global_load_dword v132, v[72:73], off offset:128
	global_load_dword v129, v[64:65], off offset:192
	global_load_dword v133, v[72:73], off offset:192
	v_mov_b32_e32 v134, v79
	v_mov_b32_e32 v135, v75
	v_mov_b32_e32 v136, v71
	v_mov_b32_e32 v137, v67
	v_mov_b64_e32 v[138:139], v[76:77]
	s_waitcnt vmcnt(24)
	v_fmac_f32_e32 v234, v242, v238
	v_fmac_f32_e32 v235, v243, v239
	v_fmac_f32_e32 v236, v244, v240
	v_fmac_f32_e32 v237, v245, v241
	global_store_dword v[220:221], v234, off
	global_store_dword v[220:221], v235, off offset:64
	global_store_dword v[220:221], v236, off offset:128
	global_store_dword v[220:221], v237, off offset:192
	v_mov_b32_e32 v75, v149
	v_add_u32_e32 v65, 0xfffff020, v98
	v_add_u32_e32 v64, v98, v168
	v_lshrrev_b32_e32 v65, 12, v65
	v_add_u32_e32 v68, 1, v65
	v_ashrrev_i32_e32 v65, 31, v64
	v_add_u32_e32 v74, 0xfffff000, v64
	v_lshlrev_b64 v[70:71], 12, v[64:65]
	v_lshlrev_b64 v[74:75], 12, v[74:75]
	v_lshl_add_u64 v[72:73], s[2:3], 0, v[70:71]
	v_cmp_gt_i32_e32 vcc, s6, v64
	v_lshl_add_u64 v[70:71], s[8:9], 0, v[70:71]
	v_lshl_add_u64 v[74:75], s[10:11], 0, v[74:75]
	v_cndmask_b32_e32 v71, v75, v71, vcc
	v_cndmask_b32_e32 v70, v74, v70, vcc
	v_cndmask_b32_e64 v65, v68, 0, vcc
	v_lshl_add_u64 v[70:71], v[70:71], 0, s[0:1]
	v_add_u32_e32 v65, s4, v65
	v_lshl_add_u64 v[66:67], v[72:73], 0, v[148:149]
	v_cndmask_b32_e64 v70, v72, v70, s[36:37]
	v_mul_lo_u32 v72, v65, s24
	v_cndmask_b32_e64 v71, v73, v71, s[36:37]
	v_ashrrev_i32_e32 v73, 31, v72
	v_lshl_add_u64 v[72:73], v[72:73], 2, s[82:83]
	v_lshl_add_u64 v[72:73], v[72:73], 0, s[0:1]
	v_lshl_add_u64 v[72:73], v[72:73], 0, v[148:149]
	v_lshl_add_u64 v[72:73], v[72:73], 0, v[160:161]
	v_lshl_add_u64 v[74:75], v[72:73], 0, s[14:15]
	v_lshl_add_u64 v[70:71], v[70:71], 0, v[148:149]
	v_add_co_u32_e32 v72, vcc, s12, v72
	v_lshl_add_u64 v[70:71], v[70:71], 0, v[160:161]
	s_nop 0
	v_addc_co_u32_e32 v73, vcc, 0, v73, vcc
	global_load_dword v234, v[70:71], off
	global_load_dword v238, v[72:73], off
	v_lshl_add_u64 v[66:67], v[66:67], 0, v[160:161]
	global_load_dword v235, v[70:71], off offset:64
	global_load_dword v239, v[74:75], off offset:64
	global_load_dword v236, v[70:71], off offset:128
	global_load_dword v240, v[74:75], off offset:128
	global_load_dword v237, v[70:71], off offset:192
	global_load_dword v241, v[74:75], off offset:192
	v_mov_b32_e32 v242, v60
	v_mov_b32_e32 v243, v56
	v_mov_b32_e32 v244, v52
	v_mov_b32_e32 v245, v48
	v_mov_b64_e32 v[220:221], v[66:67]
	s_waitcnt vmcnt(24)
	v_fmac_f32_e32 v112, v120, v116
	v_fmac_f32_e32 v113, v121, v117
	v_fmac_f32_e32 v114, v122, v118
	v_fmac_f32_e32 v115, v123, v119
	global_store_dword v[124:125], v112, off
	global_store_dword v[124:125], v113, off offset:64
	global_store_dword v[124:125], v114, off offset:128
	global_store_dword v[124:125], v115, off offset:192
	v_or_b32_e32 v66, 1, v64
	v_ashrrev_i32_e32 v67, 31, v66
	v_lshlrev_b64 v[70:71], 12, v[66:67]
	v_lshl_add_u64 v[72:73], s[2:3], 0, v[70:71]
	v_cmp_gt_i32_e32 vcc, s6, v66
	v_lshl_add_u64 v[66:67], s[8:9], 0, v[70:71]
	v_add_u32_e32 v70, 0xfffff001, v64
	v_mov_b32_e32 v71, v149
	v_lshlrev_b64 v[70:71], 12, v[70:71]
	v_cndmask_b32_e64 v48, v68, 0, vcc
	v_lshl_add_u64 v[70:71], s[10:11], 0, v[70:71]
	v_add_u32_e32 v48, s4, v48
	v_cndmask_b32_e32 v66, v70, v66, vcc
	v_mul_lo_u32 v70, v48, s24
	v_cndmask_b32_e32 v67, v71, v67, vcc
	v_ashrrev_i32_e32 v71, 31, v70
	v_lshl_add_u64 v[70:71], v[70:71], 2, s[82:83]
	v_lshl_add_u64 v[70:71], v[70:71], 0, s[0:1]
	v_lshl_add_u64 v[66:67], v[66:67], 0, s[0:1]
	v_lshl_add_u64 v[70:71], v[70:71], 0, v[148:149]
	v_cndmask_b32_e64 v67, v73, v67, s[36:37]
	v_cndmask_b32_e64 v66, v72, v66, s[36:37]
	v_lshl_add_u64 v[70:71], v[70:71], 0, v[160:161]
	v_lshl_add_u64 v[74:75], v[72:73], 0, v[148:149]
	v_lshl_add_u64 v[72:73], v[70:71], 0, s[14:15]
	v_lshl_add_u64 v[66:67], v[66:67], 0, v[148:149]
	v_add_co_u32_e32 v70, vcc, s12, v70
	v_lshl_add_u64 v[66:67], v[66:67], 0, v[160:161]
	s_nop 0
	v_addc_co_u32_e32 v71, vcc, 0, v71, vcc
	global_load_dword v112, v[66:67], off
	global_load_dword v116, v[70:71], off
	v_lshl_add_u64 v[74:75], v[74:75], 0, v[160:161]
	global_load_dword v113, v[66:67], off offset:64
	global_load_dword v117, v[72:73], off offset:64
	global_load_dword v114, v[66:67], off offset:128
	global_load_dword v118, v[72:73], off offset:128
	global_load_dword v115, v[66:67], off offset:192
	global_load_dword v119, v[72:73], off offset:192
	v_mov_b32_e32 v120, v61
	v_mov_b32_e32 v121, v57
	v_mov_b32_e32 v122, v53
	v_mov_b32_e32 v123, v49
	v_mov_b64_e32 v[124:125], v[74:75]
	s_waitcnt vmcnt(24)
	v_fmac_f32_e32 v126, v134, v130
	v_fmac_f32_e32 v127, v135, v131
	v_fmac_f32_e32 v128, v136, v132
	v_fmac_f32_e32 v129, v137, v133
	global_store_dword v[138:139], v126, off
	global_store_dword v[138:139], v127, off offset:64
	global_store_dword v[138:139], v128, off offset:128
	global_store_dword v[138:139], v129, off offset:192
	v_or_b32_e32 v48, 2, v64
	v_ashrrev_i32_e32 v49, 31, v48
	v_lshlrev_b64 v[52:53], 12, v[48:49]
	v_lshl_add_u64 v[56:57], s[2:3], 0, v[52:53]
	v_cmp_gt_i32_e32 vcc, s6, v48
	v_lshl_add_u64 v[48:49], s[8:9], 0, v[52:53]
	v_add_u32_e32 v52, 0xfffff002, v64
	v_mov_b32_e32 v53, v149
	v_lshlrev_b64 v[52:53], 12, v[52:53]
	v_lshl_add_u64 v[52:53], s[10:11], 0, v[52:53]
	v_cndmask_b32_e32 v48, v52, v48, vcc
	v_cndmask_b32_e64 v52, v68, 0, vcc
	v_add_u32_e32 v52, s4, v52
	v_mul_lo_u32 v52, v52, s24
	v_cndmask_b32_e32 v49, v53, v49, vcc
	v_ashrrev_i32_e32 v53, 31, v52
	v_lshl_add_u64 v[52:53], v[52:53], 2, s[82:83]
	v_lshl_add_u64 v[52:53], v[52:53], 0, s[0:1]
	v_lshl_add_u64 v[48:49], v[48:49], 0, s[0:1]
	v_lshl_add_u64 v[52:53], v[52:53], 0, v[148:149]
	v_cndmask_b32_e64 v49, v57, v49, s[36:37]
	v_cndmask_b32_e64 v48, v56, v48, s[36:37]
	v_lshl_add_u64 v[52:53], v[52:53], 0, v[160:161]
	v_lshl_add_u64 v[60:61], v[56:57], 0, v[148:149]
	v_lshl_add_u64 v[56:57], v[52:53], 0, s[14:15]
	v_lshl_add_u64 v[48:49], v[48:49], 0, v[148:149]
	v_add_co_u32_e32 v52, vcc, s12, v52
	v_lshl_add_u64 v[48:49], v[48:49], 0, v[160:161]
	s_nop 0
	v_addc_co_u32_e32 v53, vcc, 0, v53, vcc
	global_load_dword v126, v[48:49], off
	v_lshl_add_u64 v[60:61], v[60:61], 0, v[160:161]
	global_load_dword v130, v[52:53], off
	global_load_dword v127, v[48:49], off offset:64
	global_load_dword v131, v[56:57], off offset:64
	global_load_dword v128, v[48:49], off offset:128
	global_load_dword v132, v[56:57], off offset:128
	global_load_dword v129, v[48:49], off offset:192
	global_load_dword v133, v[56:57], off offset:192
	v_mov_b32_e32 v134, v62
	v_mov_b32_e32 v135, v58
	v_mov_b32_e32 v136, v54
	v_mov_b32_e32 v137, v50
	v_mov_b64_e32 v[138:139], v[60:61]
	s_waitcnt vmcnt(24)
	v_fmac_f32_e32 v234, v242, v238
	v_fmac_f32_e32 v235, v243, v239
	v_fmac_f32_e32 v236, v244, v240
	v_fmac_f32_e32 v237, v245, v241
	global_store_dword v[220:221], v234, off
	global_store_dword v[220:221], v235, off offset:64
	global_store_dword v[220:221], v236, off offset:128
	global_store_dword v[220:221], v237, off offset:192
	v_or_b32_e32 v48, 3, v64
	v_ashrrev_i32_e32 v49, 31, v48
	v_lshlrev_b64 v[52:53], 12, v[48:49]
	v_lshl_add_u64 v[56:57], s[2:3], 0, v[52:53]
	v_cmp_gt_i32_e32 vcc, s6, v48
	v_lshl_add_u64 v[48:49], s[8:9], 0, v[52:53]
	v_add_u32_e32 v52, 0xfffff003, v64
	v_mov_b32_e32 v53, v149
	v_lshlrev_b64 v[52:53], 12, v[52:53]
	v_cndmask_b32_e64 v50, v68, 0, vcc
	v_lshl_add_u64 v[52:53], s[10:11], 0, v[52:53]
	v_add_u32_e32 v50, s4, v50
	v_cndmask_b32_e32 v48, v52, v48, vcc
	v_mul_lo_u32 v52, v50, s24
	v_cndmask_b32_e32 v49, v53, v49, vcc
	v_ashrrev_i32_e32 v53, 31, v52
	v_lshl_add_u64 v[52:53], v[52:53], 2, s[82:83]
	v_lshl_add_u64 v[52:53], v[52:53], 0, s[0:1]
	v_lshl_add_u64 v[48:49], v[48:49], 0, s[0:1]
	v_lshl_add_u64 v[52:53], v[52:53], 0, v[148:149]
	v_cndmask_b32_e64 v49, v57, v49, s[36:37]
	v_cndmask_b32_e64 v48, v56, v48, s[36:37]
	v_lshl_add_u64 v[52:53], v[52:53], 0, v[160:161]
	v_lshl_add_u64 v[60:61], v[56:57], 0, v[148:149]
	v_lshl_add_u64 v[56:57], v[52:53], 0, s[14:15]
	v_lshl_add_u64 v[48:49], v[48:49], 0, v[148:149]
	v_add_co_u32_e32 v52, vcc, s12, v52
	v_lshl_add_u64 v[48:49], v[48:49], 0, v[160:161]
	s_nop 0
	v_addc_co_u32_e32 v53, vcc, 0, v53, vcc
	global_load_dword v234, v[48:49], off
	v_lshl_add_u64 v[60:61], v[60:61], 0, v[160:161]
	global_load_dword v238, v[52:53], off
	global_load_dword v235, v[48:49], off offset:64
	global_load_dword v239, v[56:57], off offset:64
	global_load_dword v236, v[48:49], off offset:128
	global_load_dword v240, v[56:57], off offset:128
	global_load_dword v237, v[48:49], off offset:192
	global_load_dword v241, v[56:57], off offset:192
	v_mov_b32_e32 v242, v63
	v_mov_b32_e32 v243, v59
	v_mov_b32_e32 v244, v55
	v_mov_b32_e32 v245, v51
	v_mov_b64_e32 v[220:221], v[60:61]
	s_waitcnt vmcnt(24)
	v_fmac_f32_e32 v112, v120, v116
	v_fmac_f32_e32 v113, v121, v117
	v_fmac_f32_e32 v114, v122, v118
	v_fmac_f32_e32 v115, v123, v119
	global_store_dword v[124:125], v112, off
	global_store_dword v[124:125], v113, off offset:64
	global_store_dword v[124:125], v114, off offset:128
	global_store_dword v[124:125], v115, off offset:192
	v_mov_b32_e32 v59, v149
	v_add_u32_e32 v49, 0xfffff030, v98
	v_add_u32_e32 v48, v98, v169
	v_lshrrev_b32_e32 v49, 12, v49
	v_add_u32_e32 v52, 1, v49
	v_ashrrev_i32_e32 v49, 31, v48
	v_add_u32_e32 v58, 0xfffff000, v48
	v_lshlrev_b64 v[54:55], 12, v[48:49]
	v_lshlrev_b64 v[58:59], 12, v[58:59]
	v_lshl_add_u64 v[56:57], s[2:3], 0, v[54:55]
	v_cmp_gt_i32_e32 vcc, s6, v48
	v_lshl_add_u64 v[54:55], s[8:9], 0, v[54:55]
	v_lshl_add_u64 v[58:59], s[10:11], 0, v[58:59]
	v_cndmask_b32_e32 v55, v59, v55, vcc
	v_cndmask_b32_e32 v54, v58, v54, vcc
	v_cndmask_b32_e64 v49, v52, 0, vcc
	v_lshl_add_u64 v[54:55], v[54:55], 0, s[0:1]
	v_add_u32_e32 v49, s4, v49
	v_lshl_add_u64 v[50:51], v[56:57], 0, v[148:149]
	v_cndmask_b32_e64 v54, v56, v54, s[36:37]
	v_mul_lo_u32 v56, v49, s24
	v_cndmask_b32_e64 v55, v57, v55, s[36:37]
	v_ashrrev_i32_e32 v57, 31, v56
	v_lshl_add_u64 v[56:57], v[56:57], 2, s[82:83]
	v_lshl_add_u64 v[56:57], v[56:57], 0, s[0:1]
	v_lshl_add_u64 v[56:57], v[56:57], 0, v[148:149]
	v_lshl_add_u64 v[56:57], v[56:57], 0, v[160:161]
	v_lshl_add_u64 v[58:59], v[56:57], 0, s[14:15]
	v_lshl_add_u64 v[54:55], v[54:55], 0, v[148:149]
	v_add_co_u32_e32 v56, vcc, s12, v56
	v_lshl_add_u64 v[54:55], v[54:55], 0, v[160:161]
	s_nop 0
	v_addc_co_u32_e32 v57, vcc, 0, v57, vcc
	global_load_dword v112, v[54:55], off
	global_load_dword v116, v[56:57], off
	v_lshl_add_u64 v[50:51], v[50:51], 0, v[160:161]
	global_load_dword v113, v[54:55], off offset:64
	global_load_dword v117, v[58:59], off offset:64
	global_load_dword v114, v[54:55], off offset:128
	global_load_dword v118, v[58:59], off offset:128
	global_load_dword v115, v[54:55], off offset:192
	global_load_dword v119, v[58:59], off offset:192
	v_mov_b32_e32 v120, v44
	v_mov_b32_e32 v121, v40
	v_mov_b32_e32 v122, v36
	v_mov_b32_e32 v123, v32
	v_mov_b64_e32 v[124:125], v[50:51]
	s_waitcnt vmcnt(24)
	v_fmac_f32_e32 v126, v134, v130
	v_fmac_f32_e32 v127, v135, v131
	v_fmac_f32_e32 v128, v136, v132
	v_fmac_f32_e32 v129, v137, v133
	global_store_dword v[138:139], v126, off
	global_store_dword v[138:139], v127, off offset:64
	global_store_dword v[138:139], v128, off offset:128
	global_store_dword v[138:139], v129, off offset:192
	v_or_b32_e32 v50, 1, v48
	v_ashrrev_i32_e32 v51, 31, v50
	v_lshlrev_b64 v[54:55], 12, v[50:51]
	v_lshl_add_u64 v[56:57], s[2:3], 0, v[54:55]
	v_cmp_gt_i32_e32 vcc, s6, v50
	v_lshl_add_u64 v[50:51], s[8:9], 0, v[54:55]
	v_add_u32_e32 v54, 0xfffff001, v48
	v_mov_b32_e32 v55, v149
	v_lshlrev_b64 v[54:55], 12, v[54:55]
	v_cndmask_b32_e64 v32, v52, 0, vcc
	v_lshl_add_u64 v[54:55], s[10:11], 0, v[54:55]
	v_add_u32_e32 v32, s4, v32
	v_cndmask_b32_e32 v50, v54, v50, vcc
	v_mul_lo_u32 v54, v32, s24
	v_cndmask_b32_e32 v51, v55, v51, vcc
	v_ashrrev_i32_e32 v55, 31, v54
	v_lshl_add_u64 v[54:55], v[54:55], 2, s[82:83]
	v_lshl_add_u64 v[54:55], v[54:55], 0, s[0:1]
	v_lshl_add_u64 v[50:51], v[50:51], 0, s[0:1]
	v_lshl_add_u64 v[54:55], v[54:55], 0, v[148:149]
	v_cndmask_b32_e64 v51, v57, v51, s[36:37]
	v_cndmask_b32_e64 v50, v56, v50, s[36:37]
	v_lshl_add_u64 v[54:55], v[54:55], 0, v[160:161]
	v_lshl_add_u64 v[58:59], v[56:57], 0, v[148:149]
	v_lshl_add_u64 v[56:57], v[54:55], 0, s[14:15]
	v_lshl_add_u64 v[50:51], v[50:51], 0, v[148:149]
	v_add_co_u32_e32 v54, vcc, s12, v54
	v_lshl_add_u64 v[50:51], v[50:51], 0, v[160:161]
	s_nop 0
	v_addc_co_u32_e32 v55, vcc, 0, v55, vcc
	global_load_dword v126, v[50:51], off
	global_load_dword v130, v[54:55], off
	v_lshl_add_u64 v[58:59], v[58:59], 0, v[160:161]
	global_load_dword v127, v[50:51], off offset:64
	global_load_dword v131, v[56:57], off offset:64
	global_load_dword v128, v[50:51], off offset:128
	global_load_dword v132, v[56:57], off offset:128
	global_load_dword v129, v[50:51], off offset:192
	global_load_dword v133, v[56:57], off offset:192
	v_mov_b32_e32 v134, v45
	v_mov_b32_e32 v135, v41
	v_mov_b32_e32 v136, v37
	v_mov_b32_e32 v137, v33
	v_mov_b64_e32 v[138:139], v[58:59]
	s_waitcnt vmcnt(24)
	v_fmac_f32_e32 v234, v242, v238
	v_fmac_f32_e32 v235, v243, v239
	v_fmac_f32_e32 v236, v244, v240
	v_fmac_f32_e32 v237, v245, v241
	global_store_dword v[220:221], v234, off
	global_store_dword v[220:221], v235, off offset:64
	global_store_dword v[220:221], v236, off offset:128
	global_store_dword v[220:221], v237, off offset:192
	v_or_b32_e32 v32, 2, v48
	v_ashrrev_i32_e32 v33, 31, v32
	v_lshlrev_b64 v[36:37], 12, v[32:33]
	v_lshl_add_u64 v[40:41], s[2:3], 0, v[36:37]
	v_cmp_gt_i32_e32 vcc, s6, v32
	v_lshl_add_u64 v[32:33], s[8:9], 0, v[36:37]
	v_add_u32_e32 v36, 0xfffff002, v48
	v_mov_b32_e32 v37, v149
	v_lshlrev_b64 v[36:37], 12, v[36:37]
	v_lshl_add_u64 v[36:37], s[10:11], 0, v[36:37]
	v_cndmask_b32_e32 v32, v36, v32, vcc
	v_cndmask_b32_e64 v36, v52, 0, vcc
	v_add_u32_e32 v36, s4, v36
	v_mul_lo_u32 v36, v36, s24
	v_cndmask_b32_e32 v33, v37, v33, vcc
	v_ashrrev_i32_e32 v37, 31, v36
	v_lshl_add_u64 v[36:37], v[36:37], 2, s[82:83]
	v_lshl_add_u64 v[36:37], v[36:37], 0, s[0:1]
	v_lshl_add_u64 v[32:33], v[32:33], 0, s[0:1]
	v_lshl_add_u64 v[36:37], v[36:37], 0, v[148:149]
	v_cndmask_b32_e64 v33, v41, v33, s[36:37]
	v_cndmask_b32_e64 v32, v40, v32, s[36:37]
	v_lshl_add_u64 v[36:37], v[36:37], 0, v[160:161]
	v_lshl_add_u64 v[44:45], v[40:41], 0, v[148:149]
	v_lshl_add_u64 v[40:41], v[36:37], 0, s[14:15]
	v_lshl_add_u64 v[32:33], v[32:33], 0, v[148:149]
	v_add_co_u32_e32 v36, vcc, s12, v36
	v_lshl_add_u64 v[32:33], v[32:33], 0, v[160:161]
	s_nop 0
	v_addc_co_u32_e32 v37, vcc, 0, v37, vcc
	global_load_dword v234, v[32:33], off
	v_lshl_add_u64 v[44:45], v[44:45], 0, v[160:161]
	global_load_dword v238, v[36:37], off
	global_load_dword v235, v[32:33], off offset:64
	global_load_dword v239, v[40:41], off offset:64
	global_load_dword v236, v[32:33], off offset:128
	global_load_dword v240, v[40:41], off offset:128
	global_load_dword v237, v[32:33], off offset:192
	global_load_dword v241, v[40:41], off offset:192
	v_mov_b32_e32 v242, v46
	v_mov_b32_e32 v243, v42
	v_mov_b32_e32 v244, v38
	v_mov_b32_e32 v245, v34
	v_mov_b64_e32 v[220:221], v[44:45]
	s_waitcnt vmcnt(24)
	v_fmac_f32_e32 v112, v120, v116
	v_fmac_f32_e32 v113, v121, v117
	v_fmac_f32_e32 v114, v122, v118
	v_fmac_f32_e32 v115, v123, v119
	global_store_dword v[124:125], v112, off
	global_store_dword v[124:125], v113, off offset:64
	global_store_dword v[124:125], v114, off offset:128
	global_store_dword v[124:125], v115, off offset:192
	v_or_b32_e32 v32, 3, v48
	v_ashrrev_i32_e32 v33, 31, v32
	v_lshlrev_b64 v[36:37], 12, v[32:33]
	v_lshl_add_u64 v[40:41], s[2:3], 0, v[36:37]
	v_cmp_gt_i32_e32 vcc, s6, v32
	v_lshl_add_u64 v[32:33], s[8:9], 0, v[36:37]
	v_add_u32_e32 v36, 0xfffff003, v48
	v_mov_b32_e32 v37, v149
	v_lshlrev_b64 v[36:37], 12, v[36:37]
	v_cndmask_b32_e64 v34, v52, 0, vcc
	v_lshl_add_u64 v[36:37], s[10:11], 0, v[36:37]
	v_add_u32_e32 v34, s4, v34
	v_cndmask_b32_e32 v32, v36, v32, vcc
	v_mul_lo_u32 v36, v34, s24
	v_cndmask_b32_e32 v33, v37, v33, vcc
	v_ashrrev_i32_e32 v37, 31, v36
	v_lshl_add_u64 v[36:37], v[36:37], 2, s[82:83]
	v_lshl_add_u64 v[36:37], v[36:37], 0, s[0:1]
	v_lshl_add_u64 v[32:33], v[32:33], 0, s[0:1]
	v_lshl_add_u64 v[36:37], v[36:37], 0, v[148:149]
	v_cndmask_b32_e64 v33, v41, v33, s[36:37]
	v_cndmask_b32_e64 v32, v40, v32, s[36:37]
	v_lshl_add_u64 v[36:37], v[36:37], 0, v[160:161]
	v_lshl_add_u64 v[44:45], v[40:41], 0, v[148:149]
	v_lshl_add_u64 v[40:41], v[36:37], 0, s[14:15]
	v_lshl_add_u64 v[32:33], v[32:33], 0, v[148:149]
	v_add_co_u32_e32 v36, vcc, s12, v36
	v_lshl_add_u64 v[32:33], v[32:33], 0, v[160:161]
	s_nop 0
	v_addc_co_u32_e32 v37, vcc, 0, v37, vcc
	global_load_dword v112, v[32:33], off
	v_lshl_add_u64 v[44:45], v[44:45], 0, v[160:161]
	global_load_dword v116, v[36:37], off
	global_load_dword v113, v[32:33], off offset:64
	global_load_dword v117, v[40:41], off offset:64
	global_load_dword v114, v[32:33], off offset:128
	global_load_dword v118, v[40:41], off offset:128
	global_load_dword v115, v[32:33], off offset:192
	global_load_dword v119, v[40:41], off offset:192
	v_mov_b32_e32 v120, v47
	v_mov_b32_e32 v121, v43
	v_mov_b32_e32 v122, v39
	v_mov_b32_e32 v123, v35
	v_mov_b64_e32 v[124:125], v[44:45]
	s_waitcnt vmcnt(24)
	v_fmac_f32_e32 v126, v134, v130
	v_fmac_f32_e32 v127, v135, v131
	v_fmac_f32_e32 v128, v136, v132
	v_fmac_f32_e32 v129, v137, v133
	global_store_dword v[138:139], v126, off
	global_store_dword v[138:139], v127, off offset:64
	global_store_dword v[138:139], v128, off offset:128
	global_store_dword v[138:139], v129, off offset:192
	v_mov_b32_e32 v43, v149
	v_add_u32_e32 v33, 0xfffff040, v98
	v_add_u32_e32 v32, v98, v170
	v_lshrrev_b32_e32 v33, 12, v33
	v_add_u32_e32 v36, 1, v33
	v_ashrrev_i32_e32 v33, 31, v32
	v_add_u32_e32 v42, 0xfffff000, v32
	v_lshlrev_b64 v[38:39], 12, v[32:33]
	v_lshlrev_b64 v[42:43], 12, v[42:43]
	v_lshl_add_u64 v[40:41], s[2:3], 0, v[38:39]
	v_cmp_gt_i32_e32 vcc, s6, v32
	v_lshl_add_u64 v[38:39], s[8:9], 0, v[38:39]
	v_lshl_add_u64 v[42:43], s[10:11], 0, v[42:43]
	v_cndmask_b32_e32 v39, v43, v39, vcc
	v_cndmask_b32_e32 v38, v42, v38, vcc
	v_cndmask_b32_e64 v33, v36, 0, vcc
	v_lshl_add_u64 v[38:39], v[38:39], 0, s[0:1]
	v_add_u32_e32 v33, s4, v33
	v_lshl_add_u64 v[34:35], v[40:41], 0, v[148:149]
	v_cndmask_b32_e64 v38, v40, v38, s[36:37]
	v_mul_lo_u32 v40, v33, s24
	v_cndmask_b32_e64 v39, v41, v39, s[36:37]
	v_ashrrev_i32_e32 v41, 31, v40
	v_lshl_add_u64 v[40:41], v[40:41], 2, s[82:83]
	v_lshl_add_u64 v[40:41], v[40:41], 0, s[0:1]
	v_lshl_add_u64 v[40:41], v[40:41], 0, v[148:149]
	v_lshl_add_u64 v[40:41], v[40:41], 0, v[160:161]
	v_lshl_add_u64 v[42:43], v[40:41], 0, s[14:15]
	v_lshl_add_u64 v[38:39], v[38:39], 0, v[148:149]
	v_add_co_u32_e32 v40, vcc, s12, v40
	v_lshl_add_u64 v[38:39], v[38:39], 0, v[160:161]
	s_nop 0
	v_addc_co_u32_e32 v41, vcc, 0, v41, vcc
	global_load_dword v126, v[38:39], off
	global_load_dword v130, v[40:41], off
	v_lshl_add_u64 v[34:35], v[34:35], 0, v[160:161]
	global_load_dword v127, v[38:39], off offset:64
	global_load_dword v131, v[42:43], off offset:64
	global_load_dword v128, v[38:39], off offset:128
	global_load_dword v132, v[42:43], off offset:128
	global_load_dword v129, v[38:39], off offset:192
	global_load_dword v133, v[42:43], off offset:192
	v_mov_b32_e32 v134, v28
	v_mov_b32_e32 v135, v24
	v_mov_b32_e32 v136, v20
	v_mov_b32_e32 v137, v16
	v_mov_b64_e32 v[138:139], v[34:35]
	s_waitcnt vmcnt(24)
	v_fmac_f32_e32 v234, v242, v238
	v_fmac_f32_e32 v235, v243, v239
	v_fmac_f32_e32 v236, v244, v240
	v_fmac_f32_e32 v237, v245, v241
	global_store_dword v[220:221], v234, off
	global_store_dword v[220:221], v235, off offset:64
	global_store_dword v[220:221], v236, off offset:128
	global_store_dword v[220:221], v237, off offset:192
	v_or_b32_e32 v34, 1, v32
	v_ashrrev_i32_e32 v35, 31, v34
	v_lshlrev_b64 v[38:39], 12, v[34:35]
	v_lshl_add_u64 v[40:41], s[2:3], 0, v[38:39]
	v_cmp_gt_i32_e32 vcc, s6, v34
	v_lshl_add_u64 v[34:35], s[8:9], 0, v[38:39]
	v_add_u32_e32 v38, 0xfffff001, v32
	v_mov_b32_e32 v39, v149
	v_lshlrev_b64 v[38:39], 12, v[38:39]
	v_cndmask_b32_e64 v16, v36, 0, vcc
	v_lshl_add_u64 v[38:39], s[10:11], 0, v[38:39]
	v_add_u32_e32 v16, s4, v16
	v_cndmask_b32_e32 v34, v38, v34, vcc
	v_mul_lo_u32 v38, v16, s24
	v_cndmask_b32_e32 v35, v39, v35, vcc
	v_ashrrev_i32_e32 v39, 31, v38
	v_lshl_add_u64 v[38:39], v[38:39], 2, s[82:83]
	v_lshl_add_u64 v[38:39], v[38:39], 0, s[0:1]
	v_lshl_add_u64 v[34:35], v[34:35], 0, s[0:1]
	v_lshl_add_u64 v[38:39], v[38:39], 0, v[148:149]
	v_cndmask_b32_e64 v35, v41, v35, s[36:37]
	v_cndmask_b32_e64 v34, v40, v34, s[36:37]
	v_lshl_add_u64 v[38:39], v[38:39], 0, v[160:161]
	v_lshl_add_u64 v[42:43], v[40:41], 0, v[148:149]
	v_lshl_add_u64 v[40:41], v[38:39], 0, s[14:15]
	v_lshl_add_u64 v[34:35], v[34:35], 0, v[148:149]
	v_add_co_u32_e32 v38, vcc, s12, v38
	v_lshl_add_u64 v[34:35], v[34:35], 0, v[160:161]
	s_nop 0
	v_addc_co_u32_e32 v39, vcc, 0, v39, vcc
	global_load_dword v234, v[34:35], off
	global_load_dword v238, v[38:39], off
	v_lshl_add_u64 v[42:43], v[42:43], 0, v[160:161]
	global_load_dword v235, v[34:35], off offset:64
	global_load_dword v239, v[40:41], off offset:64
	global_load_dword v236, v[34:35], off offset:128
	global_load_dword v240, v[40:41], off offset:128
	global_load_dword v237, v[34:35], off offset:192
	global_load_dword v241, v[40:41], off offset:192
	v_mov_b32_e32 v242, v29
	v_mov_b32_e32 v243, v25
	v_mov_b32_e32 v244, v21
	v_mov_b32_e32 v245, v17
	v_mov_b64_e32 v[220:221], v[42:43]
	s_waitcnt vmcnt(24)
	v_fmac_f32_e32 v112, v120, v116
	v_fmac_f32_e32 v113, v121, v117
	v_fmac_f32_e32 v114, v122, v118
	v_fmac_f32_e32 v115, v123, v119
	global_store_dword v[124:125], v112, off
	global_store_dword v[124:125], v113, off offset:64
	global_store_dword v[124:125], v114, off offset:128
	global_store_dword v[124:125], v115, off offset:192
	v_or_b32_e32 v16, 2, v32
	v_ashrrev_i32_e32 v17, 31, v16
	v_lshlrev_b64 v[20:21], 12, v[16:17]
	v_lshl_add_u64 v[24:25], s[2:3], 0, v[20:21]
	v_cmp_gt_i32_e32 vcc, s6, v16
	v_lshl_add_u64 v[16:17], s[8:9], 0, v[20:21]
	v_add_u32_e32 v20, 0xfffff002, v32
	v_mov_b32_e32 v21, v149
	v_lshlrev_b64 v[20:21], 12, v[20:21]
	v_lshl_add_u64 v[20:21], s[10:11], 0, v[20:21]
	v_cndmask_b32_e32 v16, v20, v16, vcc
	v_cndmask_b32_e64 v20, v36, 0, vcc
	v_add_u32_e32 v20, s4, v20
	v_mul_lo_u32 v20, v20, s24
	v_cndmask_b32_e32 v17, v21, v17, vcc
	v_ashrrev_i32_e32 v21, 31, v20
	v_lshl_add_u64 v[20:21], v[20:21], 2, s[82:83]
	v_lshl_add_u64 v[20:21], v[20:21], 0, s[0:1]
	v_lshl_add_u64 v[16:17], v[16:17], 0, s[0:1]
	v_lshl_add_u64 v[20:21], v[20:21], 0, v[148:149]
	v_cndmask_b32_e64 v17, v25, v17, s[36:37]
	v_cndmask_b32_e64 v16, v24, v16, s[36:37]
	v_lshl_add_u64 v[20:21], v[20:21], 0, v[160:161]
	v_lshl_add_u64 v[28:29], v[24:25], 0, v[148:149]
	v_lshl_add_u64 v[24:25], v[20:21], 0, s[14:15]
	v_lshl_add_u64 v[16:17], v[16:17], 0, v[148:149]
	v_add_co_u32_e32 v20, vcc, s12, v20
	v_lshl_add_u64 v[16:17], v[16:17], 0, v[160:161]
	s_nop 0
	v_addc_co_u32_e32 v21, vcc, 0, v21, vcc
	global_load_dword v112, v[16:17], off
	v_lshl_add_u64 v[28:29], v[28:29], 0, v[160:161]
	global_load_dword v116, v[20:21], off
	global_load_dword v113, v[16:17], off offset:64
	global_load_dword v117, v[24:25], off offset:64
	global_load_dword v114, v[16:17], off offset:128
	global_load_dword v118, v[24:25], off offset:128
	global_load_dword v115, v[16:17], off offset:192
	global_load_dword v119, v[24:25], off offset:192
	v_mov_b32_e32 v120, v30
	v_mov_b32_e32 v121, v26
	v_mov_b32_e32 v122, v22
	v_mov_b32_e32 v123, v18
	v_mov_b64_e32 v[124:125], v[28:29]
	s_waitcnt vmcnt(24)
	v_fmac_f32_e32 v126, v134, v130
	v_fmac_f32_e32 v127, v135, v131
	v_fmac_f32_e32 v128, v136, v132
	v_fmac_f32_e32 v129, v137, v133
	global_store_dword v[138:139], v126, off
	global_store_dword v[138:139], v127, off offset:64
	global_store_dword v[138:139], v128, off offset:128
	global_store_dword v[138:139], v129, off offset:192
	v_or_b32_e32 v16, 3, v32
	v_ashrrev_i32_e32 v17, 31, v16
	v_lshlrev_b64 v[20:21], 12, v[16:17]
	v_lshl_add_u64 v[24:25], s[2:3], 0, v[20:21]
	v_cmp_gt_i32_e32 vcc, s6, v16
	v_lshl_add_u64 v[16:17], s[8:9], 0, v[20:21]
	v_add_u32_e32 v20, 0xfffff003, v32
	v_mov_b32_e32 v21, v149
	v_lshlrev_b64 v[20:21], 12, v[20:21]
	v_cndmask_b32_e64 v18, v36, 0, vcc
	v_lshl_add_u64 v[20:21], s[10:11], 0, v[20:21]
	v_add_u32_e32 v18, s4, v18
	v_cndmask_b32_e32 v16, v20, v16, vcc
	v_mul_lo_u32 v20, v18, s24
	v_cndmask_b32_e32 v17, v21, v17, vcc
	v_ashrrev_i32_e32 v21, 31, v20
	v_lshl_add_u64 v[20:21], v[20:21], 2, s[82:83]
	v_lshl_add_u64 v[20:21], v[20:21], 0, s[0:1]
	v_lshl_add_u64 v[16:17], v[16:17], 0, s[0:1]
	v_lshl_add_u64 v[20:21], v[20:21], 0, v[148:149]
	v_cndmask_b32_e64 v17, v25, v17, s[36:37]
	v_cndmask_b32_e64 v16, v24, v16, s[36:37]
	v_lshl_add_u64 v[20:21], v[20:21], 0, v[160:161]
	v_lshl_add_u64 v[28:29], v[24:25], 0, v[148:149]
	v_lshl_add_u64 v[24:25], v[20:21], 0, s[14:15]
	v_lshl_add_u64 v[16:17], v[16:17], 0, v[148:149]
	v_add_co_u32_e32 v20, vcc, s12, v20
	v_lshl_add_u64 v[16:17], v[16:17], 0, v[160:161]
	s_nop 0
	v_addc_co_u32_e32 v21, vcc, 0, v21, vcc
	global_load_dword v126, v[16:17], off
	v_lshl_add_u64 v[28:29], v[28:29], 0, v[160:161]
	global_load_dword v130, v[20:21], off
	global_load_dword v127, v[16:17], off offset:64
	global_load_dword v131, v[24:25], off offset:64
	global_load_dword v128, v[16:17], off offset:128
	global_load_dword v132, v[24:25], off offset:128
	global_load_dword v129, v[16:17], off offset:192
	global_load_dword v133, v[24:25], off offset:192
	v_mov_b32_e32 v134, v31
	v_mov_b32_e32 v135, v27
	v_mov_b32_e32 v136, v23
	v_mov_b32_e32 v137, v19
	v_mov_b64_e32 v[138:139], v[28:29]
	s_waitcnt vmcnt(24)
	v_fmac_f32_e32 v234, v242, v238
	v_fmac_f32_e32 v235, v243, v239
	v_fmac_f32_e32 v236, v244, v240
	v_fmac_f32_e32 v237, v245, v241
	global_store_dword v[220:221], v234, off
	global_store_dword v[220:221], v235, off offset:64
	global_store_dword v[220:221], v236, off offset:128
	global_store_dword v[220:221], v237, off offset:192
	v_mov_b32_e32 v27, v149
	v_add_u32_e32 v17, 0xfffff050, v98
	v_add_u32_e32 v16, v98, v171
	v_lshrrev_b32_e32 v17, 12, v17
	v_add_u32_e32 v20, 1, v17
	v_ashrrev_i32_e32 v17, 31, v16
	v_add_u32_e32 v26, 0xfffff000, v16
	v_lshlrev_b64 v[22:23], 12, v[16:17]
	v_lshlrev_b64 v[26:27], 12, v[26:27]
	v_lshl_add_u64 v[24:25], s[2:3], 0, v[22:23]
	v_cmp_gt_i32_e32 vcc, s6, v16
	v_lshl_add_u64 v[22:23], s[8:9], 0, v[22:23]
	v_lshl_add_u64 v[26:27], s[10:11], 0, v[26:27]
	v_cndmask_b32_e32 v23, v27, v23, vcc
	v_cndmask_b32_e32 v22, v26, v22, vcc
	v_cndmask_b32_e64 v17, v20, 0, vcc
	v_lshl_add_u64 v[22:23], v[22:23], 0, s[0:1]
	v_add_u32_e32 v17, s4, v17
	v_lshl_add_u64 v[18:19], v[24:25], 0, v[148:149]
	v_cndmask_b32_e64 v22, v24, v22, s[36:37]
	v_mul_lo_u32 v24, v17, s24
	v_cndmask_b32_e64 v23, v25, v23, s[36:37]
	v_ashrrev_i32_e32 v25, 31, v24
	v_lshl_add_u64 v[24:25], v[24:25], 2, s[82:83]
	v_lshl_add_u64 v[24:25], v[24:25], 0, s[0:1]
	v_lshl_add_u64 v[24:25], v[24:25], 0, v[148:149]
	v_lshl_add_u64 v[24:25], v[24:25], 0, v[160:161]
	v_lshl_add_u64 v[26:27], v[24:25], 0, s[14:15]
	v_lshl_add_u64 v[22:23], v[22:23], 0, v[148:149]
	v_add_co_u32_e32 v24, vcc, s12, v24
	v_lshl_add_u64 v[22:23], v[22:23], 0, v[160:161]
	s_nop 0
	v_addc_co_u32_e32 v25, vcc, 0, v25, vcc
	global_load_dword v234, v[22:23], off
	global_load_dword v238, v[24:25], off
	v_lshl_add_u64 v[18:19], v[18:19], 0, v[160:161]
	global_load_dword v235, v[22:23], off offset:64
	global_load_dword v239, v[26:27], off offset:64
	global_load_dword v236, v[22:23], off offset:128
	global_load_dword v240, v[26:27], off offset:128
	global_load_dword v237, v[22:23], off offset:192
	global_load_dword v241, v[26:27], off offset:192
	v_mov_b32_e32 v242, v12
	v_mov_b32_e32 v243, v8
	v_mov_b32_e32 v244, v4
	v_mov_b32_e32 v245, v0
	v_mov_b64_e32 v[220:221], v[18:19]
	s_waitcnt vmcnt(24)
	v_fmac_f32_e32 v112, v120, v116
	v_fmac_f32_e32 v113, v121, v117
	v_fmac_f32_e32 v114, v122, v118
	v_fmac_f32_e32 v115, v123, v119
	global_store_dword v[124:125], v112, off
	global_store_dword v[124:125], v113, off offset:64
	global_store_dword v[124:125], v114, off offset:128
	global_store_dword v[124:125], v115, off offset:192
	v_or_b32_e32 v18, 1, v16
	v_ashrrev_i32_e32 v19, 31, v18
	v_lshlrev_b64 v[22:23], 12, v[18:19]
	v_lshl_add_u64 v[24:25], s[2:3], 0, v[22:23]
	v_cmp_gt_i32_e32 vcc, s6, v18
	v_lshl_add_u64 v[18:19], s[8:9], 0, v[22:23]
	v_add_u32_e32 v22, 0xfffff001, v16
	v_mov_b32_e32 v23, v149
	v_lshlrev_b64 v[22:23], 12, v[22:23]
	v_cndmask_b32_e64 v0, v20, 0, vcc
	v_lshl_add_u64 v[22:23], s[10:11], 0, v[22:23]
	v_add_u32_e32 v0, s4, v0
	v_cndmask_b32_e32 v18, v22, v18, vcc
	v_mul_lo_u32 v22, v0, s24
	v_cndmask_b32_e32 v19, v23, v19, vcc
	v_ashrrev_i32_e32 v23, 31, v22
	v_lshl_add_u64 v[22:23], v[22:23], 2, s[82:83]
	v_lshl_add_u64 v[22:23], v[22:23], 0, s[0:1]
	v_lshl_add_u64 v[18:19], v[18:19], 0, s[0:1]
	v_lshl_add_u64 v[22:23], v[22:23], 0, v[148:149]
	v_cndmask_b32_e64 v19, v25, v19, s[36:37]
	v_cndmask_b32_e64 v18, v24, v18, s[36:37]
	v_lshl_add_u64 v[22:23], v[22:23], 0, v[160:161]
	v_lshl_add_u64 v[26:27], v[24:25], 0, v[148:149]
	v_lshl_add_u64 v[24:25], v[22:23], 0, s[14:15]
	v_lshl_add_u64 v[18:19], v[18:19], 0, v[148:149]
	v_add_co_u32_e32 v22, vcc, s12, v22
	v_lshl_add_u64 v[18:19], v[18:19], 0, v[160:161]
	s_nop 0
	v_addc_co_u32_e32 v23, vcc, 0, v23, vcc
	global_load_dword v112, v[18:19], off
	global_load_dword v116, v[22:23], off
	v_lshl_add_u64 v[26:27], v[26:27], 0, v[160:161]
	global_load_dword v113, v[18:19], off offset:64
	global_load_dword v117, v[24:25], off offset:64
	global_load_dword v114, v[18:19], off offset:128
	global_load_dword v118, v[24:25], off offset:128
	global_load_dword v115, v[18:19], off offset:192
	global_load_dword v119, v[24:25], off offset:192
	v_mov_b32_e32 v120, v13
	v_mov_b32_e32 v121, v9
	v_mov_b32_e32 v122, v5
	v_mov_b32_e32 v123, v1
	v_mov_b64_e32 v[124:125], v[26:27]
	s_waitcnt vmcnt(24)
	v_fmac_f32_e32 v126, v134, v130
	v_fmac_f32_e32 v127, v135, v131
	v_fmac_f32_e32 v128, v136, v132
	v_fmac_f32_e32 v129, v137, v133
	global_store_dword v[138:139], v126, off
	global_store_dword v[138:139], v127, off offset:64
	global_store_dword v[138:139], v128, off offset:128
	global_store_dword v[138:139], v129, off offset:192
	v_or_b32_e32 v0, 2, v16
	v_ashrrev_i32_e32 v1, 31, v0
	v_lshlrev_b64 v[4:5], 12, v[0:1]
	v_lshl_add_u64 v[8:9], s[2:3], 0, v[4:5]
	v_cmp_gt_i32_e32 vcc, s6, v0
	v_lshl_add_u64 v[0:1], s[8:9], 0, v[4:5]
	v_add_u32_e32 v4, 0xfffff002, v16
	v_mov_b32_e32 v5, v149
	v_lshlrev_b64 v[4:5], 12, v[4:5]
	v_lshl_add_u64 v[4:5], s[10:11], 0, v[4:5]
	v_cndmask_b32_e32 v0, v4, v0, vcc
	v_cndmask_b32_e64 v4, v20, 0, vcc
	v_add_u32_e32 v4, s4, v4
	v_mul_lo_u32 v4, v4, s24
	v_cndmask_b32_e32 v1, v5, v1, vcc
	v_ashrrev_i32_e32 v5, 31, v4
	v_lshl_add_u64 v[4:5], v[4:5], 2, s[82:83]
	v_lshl_add_u64 v[4:5], v[4:5], 0, s[0:1]
	v_lshl_add_u64 v[0:1], v[0:1], 0, s[0:1]
	v_lshl_add_u64 v[4:5], v[4:5], 0, v[148:149]
	v_cndmask_b32_e64 v1, v9, v1, s[36:37]
	v_cndmask_b32_e64 v0, v8, v0, s[36:37]
	v_lshl_add_u64 v[4:5], v[4:5], 0, v[160:161]
	v_lshl_add_u64 v[12:13], v[8:9], 0, v[148:149]
	v_lshl_add_u64 v[8:9], v[4:5], 0, s[14:15]
	v_lshl_add_u64 v[0:1], v[0:1], 0, v[148:149]
	v_add_co_u32_e32 v4, vcc, s12, v4
	v_lshl_add_u64 v[0:1], v[0:1], 0, v[160:161]
	s_nop 0
	v_addc_co_u32_e32 v5, vcc, 0, v5, vcc
	global_load_dword v126, v[0:1], off
	v_lshl_add_u64 v[12:13], v[12:13], 0, v[160:161]
	global_load_dword v130, v[4:5], off
	global_load_dword v127, v[0:1], off offset:64
	global_load_dword v131, v[8:9], off offset:64
	global_load_dword v128, v[0:1], off offset:128
	global_load_dword v132, v[8:9], off offset:128
	global_load_dword v129, v[0:1], off offset:192
	global_load_dword v133, v[8:9], off offset:192
	v_mov_b32_e32 v134, v14
	v_mov_b32_e32 v135, v10
	v_mov_b32_e32 v136, v6
	v_mov_b32_e32 v137, v2
	v_mov_b64_e32 v[138:139], v[12:13]
	s_waitcnt vmcnt(24)
	v_fmac_f32_e32 v234, v242, v238
	v_fmac_f32_e32 v235, v243, v239
	v_fmac_f32_e32 v236, v244, v240
	v_fmac_f32_e32 v237, v245, v241
	global_store_dword v[220:221], v234, off
	global_store_dword v[220:221], v235, off offset:64
	global_store_dword v[220:221], v236, off offset:128
	global_store_dword v[220:221], v237, off offset:192
	v_or_b32_e32 v0, 3, v16
	v_ashrrev_i32_e32 v1, 31, v0
	v_lshlrev_b64 v[4:5], 12, v[0:1]
	v_lshl_add_u64 v[8:9], s[2:3], 0, v[4:5]
	v_cmp_gt_i32_e32 vcc, s6, v0
	v_lshl_add_u64 v[0:1], s[8:9], 0, v[4:5]
	v_add_u32_e32 v4, 0xfffff003, v16
	v_mov_b32_e32 v5, v149
	v_lshlrev_b64 v[4:5], 12, v[4:5]
	v_cndmask_b32_e64 v2, v20, 0, vcc
	v_lshl_add_u64 v[4:5], s[10:11], 0, v[4:5]
	v_add_u32_e32 v2, s4, v2
	v_cndmask_b32_e32 v0, v4, v0, vcc
	v_mul_lo_u32 v4, v2, s24
	v_cndmask_b32_e32 v1, v5, v1, vcc
	v_ashrrev_i32_e32 v5, 31, v4
	v_lshl_add_u64 v[4:5], v[4:5], 2, s[82:83]
	v_lshl_add_u64 v[4:5], v[4:5], 0, s[0:1]
	v_lshl_add_u64 v[0:1], v[0:1], 0, s[0:1]
	v_lshl_add_u64 v[4:5], v[4:5], 0, v[148:149]
	v_cndmask_b32_e64 v1, v9, v1, s[36:37]
	v_cndmask_b32_e64 v0, v8, v0, s[36:37]
	v_lshl_add_u64 v[4:5], v[4:5], 0, v[160:161]
	v_lshl_add_u64 v[12:13], v[8:9], 0, v[148:149]
	v_lshl_add_u64 v[8:9], v[4:5], 0, s[14:15]
	v_lshl_add_u64 v[0:1], v[0:1], 0, v[148:149]
	v_add_co_u32_e32 v4, vcc, s12, v4
	v_lshl_add_u64 v[0:1], v[0:1], 0, v[160:161]
	s_nop 0
	v_addc_co_u32_e32 v5, vcc, 0, v5, vcc
	global_load_dword v234, v[0:1], off
	v_lshl_add_u64 v[12:13], v[12:13], 0, v[160:161]
	global_load_dword v238, v[4:5], off
	global_load_dword v235, v[0:1], off offset:64
	global_load_dword v239, v[8:9], off offset:64
	global_load_dword v236, v[0:1], off offset:128
	global_load_dword v240, v[8:9], off offset:128
	global_load_dword v237, v[0:1], off offset:192
	global_load_dword v241, v[8:9], off offset:192
	v_mov_b32_e32 v242, v15
	v_mov_b32_e32 v243, v11
	v_mov_b32_e32 v244, v7
	v_mov_b32_e32 v245, v3
	v_mov_b64_e32 v[220:221], v[12:13]
	s_waitcnt vmcnt(24)
	v_fmac_f32_e32 v112, v120, v116
	v_fmac_f32_e32 v113, v121, v117
	v_fmac_f32_e32 v114, v122, v118
	v_fmac_f32_e32 v115, v123, v119
	global_store_dword v[124:125], v112, off
	global_store_dword v[124:125], v113, off offset:64
	global_store_dword v[124:125], v114, off offset:128
	global_store_dword v[124:125], v115, off offset:192
	s_waitcnt vmcnt(16)
	v_fmac_f32_e32 v126, v134, v130
	v_fmac_f32_e32 v127, v135, v131
	v_fmac_f32_e32 v128, v136, v132
	v_fmac_f32_e32 v129, v137, v133
	global_store_dword v[138:139], v126, off
	global_store_dword v[138:139], v127, off offset:64
	global_store_dword v[138:139], v128, off offset:128
	global_store_dword v[138:139], v129, off offset:192
	s_waitcnt vmcnt(8)
	v_fmac_f32_e32 v234, v242, v238
	v_fmac_f32_e32 v235, v243, v239
	v_fmac_f32_e32 v236, v244, v240
	v_fmac_f32_e32 v237, v245, v241
	global_store_dword v[220:221], v234, off
	global_store_dword v[220:221], v235, off offset:64
	global_store_dword v[220:221], v236, off offset:128
	global_store_dword v[220:221], v237, off offset:192
	s_cbranch_scc0 .LBB0_1136
